# EpiSwiGLU epilogues regenerated: packed scale and *u multiplies, transcendental results consumed two slots later so no s_nop (8 issue slots per output pair instead of ~14)
# speedup vs baseline: 1.0074x; 1.0074x over previous
.LBB0_797:
	s_mov_b32 s98, 0xbfb8aa3b
	s_mov_b32 s99, 0xbfb8aa3b
	s_lshl_b32 s10, s40, 7
	s_or_b32 s8, s35, s10
	v_or_b32_e32 v138, s8, v131
	v_add_u32_e32 v140, 0x4000, v1
	v_pk_mul_f32 v[230:231], v[126:127], s[98:99]
	v_exp_f32_e32 v230, v230
	v_exp_f32_e32 v231, v231
	v_add_f32_e32 v230, 1.0, v230
	v_add_f32_e32 v231, 1.0, v231
	v_rcp_f32_e32 v230, v230
	v_rcp_f32_e32 v231, v231
	v_mul_f32_e32 v234, v126, v230
	v_mul_f32_e32 v235, v127, v231
	v_pk_mul_f32 v[234:235], v[234:235], v[122:123]
	v_cvt_pk_bf16_f32 v122, v234, v235
	v_pk_mul_f32 v[230:231], v[128:129], s[98:99]
	v_exp_f32_e32 v230, v230
	v_exp_f32_e32 v231, v231
	v_add_f32_e32 v230, 1.0, v230
	v_add_f32_e32 v231, 1.0, v231
	v_rcp_f32_e32 v230, v230
	v_rcp_f32_e32 v231, v231
	v_mul_f32_e32 v236, v128, v230
	v_mul_f32_e32 v237, v129, v231
	v_pk_mul_f32 v[236:237], v[236:237], v[124:125]
	v_cvt_pk_bf16_f32 v123, v236, v237
	v_pk_mul_f32 v[230:231], v[118:119], s[98:99]
	v_exp_f32_e32 v230, v230
	v_exp_f32_e32 v231, v231
	v_add_f32_e32 v230, 1.0, v230
	v_add_f32_e32 v231, 1.0, v231
	v_rcp_f32_e32 v230, v230
	v_rcp_f32_e32 v231, v231
	v_mul_f32_e32 v238, v118, v230
	v_mul_f32_e32 v239, v119, v231
	v_pk_mul_f32 v[238:239], v[238:239], v[114:115]
	v_cvt_pk_bf16_f32 v124, v238, v239
	v_pk_mul_f32 v[230:231], v[120:121], s[98:99]
	v_exp_f32_e32 v230, v230
	v_exp_f32_e32 v231, v231
	v_add_f32_e32 v230, 1.0, v230
	v_add_f32_e32 v231, 1.0, v231
	v_rcp_f32_e32 v230, v230
	v_rcp_f32_e32 v231, v231
	v_mul_f32_e32 v240, v120, v230
	v_mul_f32_e32 v241, v121, v231
	v_pk_mul_f32 v[240:241], v[240:241], v[116:117]
	v_cvt_pk_bf16_f32 v125, v240, v241
	v_ashrrev_i32_e32 v139, 31, v138
	s_movk_i32 s8, 0x1600
	v_mov_b64_e32 v[114:115], s[16:17]
	v_mad_i64_i32 v[118:119], s[10:11], v140, s8, v[114:115]
	v_lshlrev_b64 v[116:117], 1, v[138:139]
	v_lshl_add_u64 v[118:119], v[118:119], 0, v[116:117]
	global_store_dwordx4 v[118:119], v[122:125], off
	s_nop 1
	v_pk_mul_f32 v[230:231], v[110:111], s[98:99]
	v_exp_f32_e32 v230, v230
	v_exp_f32_e32 v231, v231
	v_add_f32_e32 v230, 1.0, v230
	v_add_f32_e32 v231, 1.0, v231
	v_rcp_f32_e32 v230, v230
	v_rcp_f32_e32 v231, v231
	v_mul_f32_e32 v234, v110, v230
	v_mul_f32_e32 v235, v111, v231
	v_pk_mul_f32 v[234:235], v[234:235], v[106:107]
	v_cvt_pk_bf16_f32 v106, v234, v235
	v_pk_mul_f32 v[230:231], v[112:113], s[98:99]
	v_exp_f32_e32 v230, v230
	v_exp_f32_e32 v231, v231
	v_add_f32_e32 v230, 1.0, v230
	v_add_f32_e32 v231, 1.0, v231
	v_rcp_f32_e32 v230, v230
	v_rcp_f32_e32 v231, v231
	v_mul_f32_e32 v236, v112, v230
	v_mul_f32_e32 v237, v113, v231
	v_pk_mul_f32 v[236:237], v[236:237], v[108:109]
	v_cvt_pk_bf16_f32 v107, v236, v237
	v_pk_mul_f32 v[230:231], v[102:103], s[98:99]
	v_exp_f32_e32 v230, v230
	v_exp_f32_e32 v231, v231
	v_add_f32_e32 v230, 1.0, v230
	v_add_f32_e32 v231, 1.0, v231
	v_rcp_f32_e32 v230, v230
	v_rcp_f32_e32 v231, v231
	v_mul_f32_e32 v238, v102, v230
	v_mul_f32_e32 v239, v103, v231
	v_pk_mul_f32 v[238:239], v[238:239], v[98:99]
	v_cvt_pk_bf16_f32 v108, v238, v239
	v_pk_mul_f32 v[230:231], v[104:105], s[98:99]
	v_exp_f32_e32 v230, v230
	v_exp_f32_e32 v231, v231
	v_add_f32_e32 v230, 1.0, v230
	v_add_f32_e32 v231, 1.0, v231
	v_rcp_f32_e32 v230, v230
	v_rcp_f32_e32 v231, v231
	v_mul_f32_e32 v240, v104, v230
	v_mul_f32_e32 v241, v105, v231
	v_pk_mul_f32 v[240:241], v[240:241], v[100:101]
	v_cvt_pk_bf16_f32 v109, v240, v241
	v_add_u32_e32 v98, 0x4010, v1
	v_mad_i64_i32 v[98:99], s[10:11], v98, s8, v[114:115]
	v_lshl_add_u64 v[98:99], v[98:99], 0, v[116:117]
	global_store_dwordx4 v[98:99], v[106:109], off
	v_pk_mul_f32 v[230:231], v[94:95], s[98:99]
	v_exp_f32_e32 v230, v230
	v_exp_f32_e32 v231, v231
	v_add_f32_e32 v230, 1.0, v230
	v_add_f32_e32 v231, 1.0, v231
	v_rcp_f32_e32 v230, v230
	v_rcp_f32_e32 v231, v231
	v_mul_f32_e32 v234, v94, v230
	v_mul_f32_e32 v235, v95, v231
	v_pk_mul_f32 v[234:235], v[234:235], v[90:91]
	v_cvt_pk_bf16_f32 v90, v234, v235
	v_pk_mul_f32 v[230:231], v[96:97], s[98:99]
	v_exp_f32_e32 v230, v230
	v_exp_f32_e32 v231, v231
	v_add_f32_e32 v230, 1.0, v230
	v_add_f32_e32 v231, 1.0, v231
	v_rcp_f32_e32 v230, v230
	v_rcp_f32_e32 v231, v231
	v_mul_f32_e32 v236, v96, v230
	v_mul_f32_e32 v237, v97, v231
	v_pk_mul_f32 v[236:237], v[236:237], v[92:93]
	v_cvt_pk_bf16_f32 v91, v236, v237
	v_pk_mul_f32 v[230:231], v[86:87], s[98:99]
	v_exp_f32_e32 v230, v230
	v_exp_f32_e32 v231, v231
	v_add_f32_e32 v230, 1.0, v230
	v_add_f32_e32 v231, 1.0, v231
	v_rcp_f32_e32 v230, v230
	v_rcp_f32_e32 v231, v231
	v_mul_f32_e32 v238, v86, v230
	v_mul_f32_e32 v239, v87, v231
	v_pk_mul_f32 v[238:239], v[238:239], v[82:83]
	v_cvt_pk_bf16_f32 v92, v238, v239
	v_pk_mul_f32 v[230:231], v[88:89], s[98:99]
	v_exp_f32_e32 v230, v230
	v_exp_f32_e32 v231, v231
	v_add_f32_e32 v230, 1.0, v230
	v_add_f32_e32 v231, 1.0, v231
	v_rcp_f32_e32 v230, v230
	v_rcp_f32_e32 v231, v231
	v_mul_f32_e32 v240, v88, v230
	v_mul_f32_e32 v241, v89, v231
	v_pk_mul_f32 v[240:241], v[240:241], v[84:85]
	v_cvt_pk_bf16_f32 v93, v240, v241
	v_add_u32_e32 v82, 0x4020, v1
	v_mad_i64_i32 v[82:83], s[10:11], v82, s8, v[114:115]
	v_lshl_add_u64 v[82:83], v[82:83], 0, v[116:117]
	global_store_dwordx4 v[82:83], v[90:93], off
	v_pk_mul_f32 v[230:231], v[78:79], s[98:99]
	v_exp_f32_e32 v230, v230
	v_exp_f32_e32 v231, v231
	v_add_f32_e32 v230, 1.0, v230
	v_add_f32_e32 v231, 1.0, v231
	v_rcp_f32_e32 v230, v230
	v_rcp_f32_e32 v231, v231
	v_mul_f32_e32 v234, v78, v230
	v_mul_f32_e32 v235, v79, v231
	v_pk_mul_f32 v[234:235], v[234:235], v[74:75]
	v_cvt_pk_bf16_f32 v74, v234, v235
	v_pk_mul_f32 v[230:231], v[80:81], s[98:99]
	v_exp_f32_e32 v230, v230
	v_exp_f32_e32 v231, v231
	v_add_f32_e32 v230, 1.0, v230
	v_add_f32_e32 v231, 1.0, v231
	v_rcp_f32_e32 v230, v230
	v_rcp_f32_e32 v231, v231
	v_mul_f32_e32 v236, v80, v230
	v_mul_f32_e32 v237, v81, v231
	v_pk_mul_f32 v[236:237], v[236:237], v[76:77]
	v_cvt_pk_bf16_f32 v75, v236, v237
	v_pk_mul_f32 v[230:231], v[70:71], s[98:99]
	v_exp_f32_e32 v230, v230
	v_exp_f32_e32 v231, v231
	v_add_f32_e32 v230, 1.0, v230
	v_add_f32_e32 v231, 1.0, v231
	v_rcp_f32_e32 v230, v230
	v_rcp_f32_e32 v231, v231
	v_mul_f32_e32 v238, v70, v230
	v_mul_f32_e32 v239, v71, v231
	v_pk_mul_f32 v[238:239], v[238:239], v[66:67]
	v_cvt_pk_bf16_f32 v76, v238, v239
	v_pk_mul_f32 v[230:231], v[72:73], s[98:99]
	v_exp_f32_e32 v230, v230
	v_exp_f32_e32 v231, v231
	v_add_f32_e32 v230, 1.0, v230
	v_add_f32_e32 v231, 1.0, v231
	v_rcp_f32_e32 v230, v230
	v_rcp_f32_e32 v231, v231
	v_mul_f32_e32 v240, v72, v230
	v_mul_f32_e32 v241, v73, v231
	v_pk_mul_f32 v[240:241], v[240:241], v[68:69]
	v_cvt_pk_bf16_f32 v77, v240, v241
	v_add_u32_e32 v66, 0x4030, v1
	v_mad_i64_i32 v[66:67], s[10:11], v66, s8, v[114:115]
	v_lshl_add_u64 v[66:67], v[66:67], 0, v[116:117]
	global_store_dwordx4 v[66:67], v[74:77], off
	v_pk_mul_f32 v[230:231], v[62:63], s[98:99]
	v_exp_f32_e32 v230, v230
	v_exp_f32_e32 v231, v231
	v_add_f32_e32 v230, 1.0, v230
	v_add_f32_e32 v231, 1.0, v231
	v_rcp_f32_e32 v230, v230
	v_rcp_f32_e32 v231, v231
	v_mul_f32_e32 v234, v62, v230
	v_mul_f32_e32 v235, v63, v231
	v_pk_mul_f32 v[234:235], v[234:235], v[58:59]
	v_cvt_pk_bf16_f32 v58, v234, v235
	v_pk_mul_f32 v[230:231], v[64:65], s[98:99]
	v_exp_f32_e32 v230, v230
	v_exp_f32_e32 v231, v231
	v_add_f32_e32 v230, 1.0, v230
	v_add_f32_e32 v231, 1.0, v231
	v_rcp_f32_e32 v230, v230
	v_rcp_f32_e32 v231, v231
	v_mul_f32_e32 v236, v64, v230
	v_mul_f32_e32 v237, v65, v231
	v_pk_mul_f32 v[236:237], v[236:237], v[60:61]
	v_cvt_pk_bf16_f32 v59, v236, v237
	v_pk_mul_f32 v[230:231], v[54:55], s[98:99]
	v_exp_f32_e32 v230, v230
	v_exp_f32_e32 v231, v231
	v_add_f32_e32 v230, 1.0, v230
	v_add_f32_e32 v231, 1.0, v231
	v_rcp_f32_e32 v230, v230
	v_rcp_f32_e32 v231, v231
	v_mul_f32_e32 v238, v54, v230
	v_mul_f32_e32 v239, v55, v231
	v_pk_mul_f32 v[238:239], v[238:239], v[50:51]
	v_cvt_pk_bf16_f32 v60, v238, v239
	v_pk_mul_f32 v[230:231], v[56:57], s[98:99]
	v_exp_f32_e32 v230, v230
	v_exp_f32_e32 v231, v231
	v_add_f32_e32 v230, 1.0, v230
	v_add_f32_e32 v231, 1.0, v231
	v_rcp_f32_e32 v230, v230
	v_rcp_f32_e32 v231, v231
	v_mul_f32_e32 v240, v56, v230
	v_mul_f32_e32 v241, v57, v231
	v_pk_mul_f32 v[240:241], v[240:241], v[52:53]
	v_add_u32_e32 v66, 0x4080, v1
	v_cvt_pk_bf16_f32 v61, v240, v241
	v_mad_i64_i32 v[50:51], s[10:11], v66, s8, v[114:115]
	v_lshl_add_u64 v[50:51], v[50:51], 0, v[116:117]
	global_store_dwordx4 v[50:51], v[58:61], off
	v_pk_mul_f32 v[230:231], v[46:47], s[98:99]
	v_exp_f32_e32 v230, v230
	v_exp_f32_e32 v231, v231
	v_add_f32_e32 v230, 1.0, v230
	v_add_f32_e32 v231, 1.0, v231
	v_rcp_f32_e32 v230, v230
	v_rcp_f32_e32 v231, v231
	v_mul_f32_e32 v234, v46, v230
	v_mul_f32_e32 v235, v47, v231
	v_pk_mul_f32 v[234:235], v[234:235], v[42:43]
	v_cvt_pk_bf16_f32 v42, v234, v235
	v_pk_mul_f32 v[230:231], v[48:49], s[98:99]
	v_exp_f32_e32 v230, v230
	v_exp_f32_e32 v231, v231
	v_add_f32_e32 v230, 1.0, v230
	v_add_f32_e32 v231, 1.0, v231
	v_rcp_f32_e32 v230, v230
	v_rcp_f32_e32 v231, v231
	v_mul_f32_e32 v236, v48, v230
	v_mul_f32_e32 v237, v49, v231
	v_pk_mul_f32 v[236:237], v[236:237], v[44:45]
	v_cvt_pk_bf16_f32 v43, v236, v237
	v_pk_mul_f32 v[230:231], v[38:39], s[98:99]
	v_exp_f32_e32 v230, v230
	v_exp_f32_e32 v231, v231
	v_add_f32_e32 v230, 1.0, v230
	v_add_f32_e32 v231, 1.0, v231
	v_rcp_f32_e32 v230, v230
	v_rcp_f32_e32 v231, v231
	v_mul_f32_e32 v238, v38, v230
	v_mul_f32_e32 v239, v39, v231
	v_pk_mul_f32 v[238:239], v[238:239], v[34:35]
	v_cvt_pk_bf16_f32 v44, v238, v239
	v_pk_mul_f32 v[230:231], v[40:41], s[98:99]
	v_exp_f32_e32 v230, v230
	v_exp_f32_e32 v231, v231
	v_add_f32_e32 v230, 1.0, v230
	v_add_f32_e32 v231, 1.0, v231
	v_rcp_f32_e32 v230, v230
	v_rcp_f32_e32 v231, v231
	v_mul_f32_e32 v240, v40, v230
	v_mul_f32_e32 v241, v41, v231
	v_pk_mul_f32 v[240:241], v[240:241], v[36:37]
	v_cvt_pk_bf16_f32 v45, v240, v241
	v_add_u32_e32 v34, 0x4090, v1
	v_mad_i64_i32 v[34:35], s[10:11], v34, s8, v[114:115]
	v_lshl_add_u64 v[34:35], v[34:35], 0, v[116:117]
	global_store_dwordx4 v[34:35], v[42:45], off
	v_pk_mul_f32 v[230:231], v[30:31], s[98:99]
	v_exp_f32_e32 v230, v230
	v_exp_f32_e32 v231, v231
	v_add_f32_e32 v230, 1.0, v230
	v_add_f32_e32 v231, 1.0, v231
	v_rcp_f32_e32 v230, v230
	v_rcp_f32_e32 v231, v231
	v_mul_f32_e32 v234, v30, v230
	v_mul_f32_e32 v235, v31, v231
	v_pk_mul_f32 v[234:235], v[234:235], v[26:27]
	v_cvt_pk_bf16_f32 v26, v234, v235
	v_pk_mul_f32 v[230:231], v[32:33], s[98:99]
	v_exp_f32_e32 v230, v230
	v_exp_f32_e32 v231, v231
	v_add_f32_e32 v230, 1.0, v230
	v_add_f32_e32 v231, 1.0, v231
	v_rcp_f32_e32 v230, v230
	v_rcp_f32_e32 v231, v231
	v_mul_f32_e32 v236, v32, v230
	v_mul_f32_e32 v237, v33, v231
	v_pk_mul_f32 v[236:237], v[236:237], v[28:29]
	v_cvt_pk_bf16_f32 v27, v236, v237
	v_pk_mul_f32 v[230:231], v[22:23], s[98:99]
	v_exp_f32_e32 v230, v230
	v_exp_f32_e32 v231, v231
	v_add_f32_e32 v230, 1.0, v230
	v_add_f32_e32 v231, 1.0, v231
	v_rcp_f32_e32 v230, v230
	v_rcp_f32_e32 v231, v231
	v_mul_f32_e32 v238, v22, v230
	v_mul_f32_e32 v239, v23, v231
	v_pk_mul_f32 v[238:239], v[238:239], v[18:19]
	v_cvt_pk_bf16_f32 v28, v238, v239
	v_pk_mul_f32 v[230:231], v[24:25], s[98:99]
	v_exp_f32_e32 v230, v230
	v_exp_f32_e32 v231, v231
	v_add_f32_e32 v230, 1.0, v230
	v_add_f32_e32 v231, 1.0, v231
	v_rcp_f32_e32 v230, v230
	v_rcp_f32_e32 v231, v231
	v_mul_f32_e32 v240, v24, v230
	v_mul_f32_e32 v241, v25, v231
	v_pk_mul_f32 v[240:241], v[240:241], v[20:21]
	v_cvt_pk_bf16_f32 v29, v240, v241
	v_add_u32_e32 v18, 0x40a0, v1
	v_mad_i64_i32 v[18:19], s[10:11], v18, s8, v[114:115]
	v_lshl_add_u64 v[18:19], v[18:19], 0, v[116:117]
	global_store_dwordx4 v[18:19], v[26:29], off
	v_pk_mul_f32 v[230:231], v[14:15], s[98:99]
	v_exp_f32_e32 v230, v230
	v_exp_f32_e32 v231, v231
	v_add_f32_e32 v230, 1.0, v230
	v_add_f32_e32 v231, 1.0, v231
	v_rcp_f32_e32 v230, v230
	v_rcp_f32_e32 v231, v231
	v_mul_f32_e32 v234, v14, v230
	v_mul_f32_e32 v235, v15, v231
	v_pk_mul_f32 v[234:235], v[234:235], v[10:11]
	v_cvt_pk_bf16_f32 v10, v234, v235
	v_pk_mul_f32 v[230:231], v[16:17], s[98:99]
	v_exp_f32_e32 v230, v230
	v_exp_f32_e32 v231, v231
	v_add_f32_e32 v230, 1.0, v230
	v_add_f32_e32 v231, 1.0, v231
	v_rcp_f32_e32 v230, v230
	v_rcp_f32_e32 v231, v231
	v_mul_f32_e32 v236, v16, v230
	v_mul_f32_e32 v237, v17, v231
	v_pk_mul_f32 v[236:237], v[236:237], v[12:13]
	v_cvt_pk_bf16_f32 v11, v236, v237
	v_pk_mul_f32 v[230:231], v[6:7], s[98:99]
	v_exp_f32_e32 v230, v230
	v_exp_f32_e32 v231, v231
	v_add_f32_e32 v230, 1.0, v230
	v_add_f32_e32 v231, 1.0, v231
	v_rcp_f32_e32 v230, v230
	v_rcp_f32_e32 v231, v231
	v_mul_f32_e32 v238, v6, v230
	v_mul_f32_e32 v239, v7, v231
	v_pk_mul_f32 v[238:239], v[238:239], v[2:3]
	v_cvt_pk_bf16_f32 v12, v238, v239
	v_pk_mul_f32 v[230:231], v[8:9], s[98:99]
	v_exp_f32_e32 v230, v230
	v_exp_f32_e32 v231, v231
	v_add_f32_e32 v230, 1.0, v230
	v_add_f32_e32 v231, 1.0, v231
	v_rcp_f32_e32 v230, v230
	v_rcp_f32_e32 v231, v231
	v_mul_f32_e32 v240, v8, v230
	v_mul_f32_e32 v241, v9, v231
	v_pk_mul_f32 v[240:241], v[240:241], v[4:5]
	v_add_u32_e32 v1, 0x40b0, v1
	v_cvt_pk_bf16_f32 v13, v240, v241
	v_mad_i64_i32 v[2:3], s[8:9], v1, s8, v[114:115]
	v_lshl_add_u64 v[2:3], v[2:3], 0, v[116:117]
	global_store_dwordx4 v[2:3], v[10:13], off
	s_waitcnt vmcnt(0)
	s_barrier
	s_waitcnt vmcnt(0)
	s_waitcnt vmcnt(0) lgkmcnt(0)
	s_barrier
	s_mov_b64 s[8:9], exec
	v_readlane_b32 s10, v228, 2
	v_readlane_b32 s11, v228, 3
	s_and_b64 s[10:11], s[8:9], s[10:11]
	s_mov_b64 exec, s[10:11]
	s_cbranch_execz .LBB0_800
	s_mov_b64 s[10:11], exec
	v_mbcnt_lo_u32_b32 v1, s10, 0
	buffer_wbl2 sc1
	s_waitcnt vmcnt(0)
	v_mbcnt_hi_u32_b32 v1, s11, v1
	v_cmp_eq_u32_e32 vcc, 0, v1
	s_and_b64 s[18:19], exec, vcc
	s_mov_b64 exec, s[18:19]
	s_cbranch_execz .LBB0_800
	s_bcnt1_i32_b64 s10, s[10:11]
	v_mov_b32_e32 v1, 0
	v_mov_b32_e32 v2, s10
	global_atomic_add v1, v2, s[6:7]

.LBB0_863:
	s_mov_b32 s98, 0xbfb8aa3b
	s_mov_b32 s99, 0xbfb8aa3b
	v_lshl_or_b32 v156, s65, 7, v131
	v_lshl_add_u32 v154, s50, 8, v1
	v_pk_mul_f32 v[230:231], v[126:127], s[98:99]
	v_exp_f32_e32 v230, v230
	v_exp_f32_e32 v231, v231
	v_add_f32_e32 v230, 1.0, v230
	v_add_f32_e32 v231, 1.0, v231
	v_rcp_f32_e32 v230, v230
	v_rcp_f32_e32 v231, v231
	v_mul_f32_e32 v234, v126, v230
	v_mul_f32_e32 v235, v127, v231
	v_pk_mul_f32 v[234:235], v[234:235], v[122:123]
	v_cvt_pk_bf16_f32 v122, v234, v235
	v_pk_mul_f32 v[230:231], v[128:129], s[98:99]
	v_exp_f32_e32 v230, v230
	v_exp_f32_e32 v231, v231
	v_add_f32_e32 v230, 1.0, v230
	v_add_f32_e32 v231, 1.0, v231
	v_rcp_f32_e32 v230, v230
	v_rcp_f32_e32 v231, v231
	v_mul_f32_e32 v236, v128, v230
	v_mul_f32_e32 v237, v129, v231
	v_pk_mul_f32 v[236:237], v[236:237], v[124:125]
	v_cvt_pk_bf16_f32 v123, v236, v237
	v_pk_mul_f32 v[230:231], v[118:119], s[98:99]
	v_exp_f32_e32 v230, v230
	v_exp_f32_e32 v231, v231
	v_add_f32_e32 v230, 1.0, v230
	v_add_f32_e32 v231, 1.0, v231
	v_rcp_f32_e32 v230, v230
	v_rcp_f32_e32 v231, v231
	v_mul_f32_e32 v238, v118, v230
	v_mul_f32_e32 v239, v119, v231
	v_pk_mul_f32 v[238:239], v[238:239], v[114:115]
	v_cvt_pk_bf16_f32 v124, v238, v239
	v_pk_mul_f32 v[230:231], v[120:121], s[98:99]
	v_exp_f32_e32 v230, v230
	v_exp_f32_e32 v231, v231
	v_add_f32_e32 v230, 1.0, v230
	v_add_f32_e32 v231, 1.0, v231
	v_rcp_f32_e32 v230, v230
	v_rcp_f32_e32 v231, v231
	v_mul_f32_e32 v240, v120, v230
	v_mul_f32_e32 v241, v121, v231
	v_pk_mul_f32 v[240:241], v[240:241], v[116:117]
	v_cvt_pk_bf16_f32 v125, v240, v241
	v_ashrrev_i32_e32 v157, 31, v156
	v_mov_b64_e32 v[114:115], s[16:17]
	v_mad_i64_i32 v[118:119], s[52:53], v154, s64, v[114:115]
	v_lshlrev_b64 v[116:117], 1, v[156:157]
	v_lshl_add_u64 v[118:119], v[118:119], 0, v[116:117]
	global_store_dwordx4 v[118:119], v[122:125], off
	s_nop 1
	v_pk_mul_f32 v[230:231], v[110:111], s[98:99]
	v_exp_f32_e32 v230, v230
	v_exp_f32_e32 v231, v231
	v_add_f32_e32 v230, 1.0, v230
	v_add_f32_e32 v231, 1.0, v231
	v_rcp_f32_e32 v230, v230
	v_rcp_f32_e32 v231, v231
	v_mul_f32_e32 v234, v110, v230
	v_mul_f32_e32 v235, v111, v231
	v_pk_mul_f32 v[234:235], v[234:235], v[106:107]
	v_cvt_pk_bf16_f32 v106, v234, v235
	v_pk_mul_f32 v[230:231], v[112:113], s[98:99]
	v_exp_f32_e32 v230, v230
	v_exp_f32_e32 v231, v231
	v_add_f32_e32 v230, 1.0, v230
	v_add_f32_e32 v231, 1.0, v231
	v_rcp_f32_e32 v230, v230
	v_rcp_f32_e32 v231, v231
	v_mul_f32_e32 v236, v112, v230
	v_mul_f32_e32 v237, v113, v231
	v_pk_mul_f32 v[236:237], v[236:237], v[108:109]
	v_cvt_pk_bf16_f32 v107, v236, v237
	v_pk_mul_f32 v[230:231], v[102:103], s[98:99]
	v_exp_f32_e32 v230, v230
	v_exp_f32_e32 v231, v231
	v_add_f32_e32 v230, 1.0, v230
	v_add_f32_e32 v231, 1.0, v231
	v_rcp_f32_e32 v230, v230
	v_rcp_f32_e32 v231, v231
	v_mul_f32_e32 v238, v102, v230
	v_mul_f32_e32 v239, v103, v231
	v_pk_mul_f32 v[238:239], v[238:239], v[98:99]
	v_cvt_pk_bf16_f32 v108, v238, v239
	v_pk_mul_f32 v[230:231], v[104:105], s[98:99]
	v_exp_f32_e32 v230, v230
	v_exp_f32_e32 v231, v231
	v_add_f32_e32 v230, 1.0, v230
	v_add_f32_e32 v231, 1.0, v231
	v_rcp_f32_e32 v230, v230
	v_rcp_f32_e32 v231, v231
	v_mul_f32_e32 v240, v104, v230
	v_mul_f32_e32 v241, v105, v231
	v_pk_mul_f32 v[240:241], v[240:241], v[100:101]
	v_cvt_pk_bf16_f32 v109, v240, v241
	v_or_b32_e32 v98, 16, v154
	v_mad_i64_i32 v[98:99], s[52:53], v98, s64, v[114:115]
	v_lshl_add_u64 v[98:99], v[98:99], 0, v[116:117]
	global_store_dwordx4 v[98:99], v[106:109], off
	v_pk_mul_f32 v[230:231], v[94:95], s[98:99]
	v_exp_f32_e32 v230, v230
	v_exp_f32_e32 v231, v231
	v_add_f32_e32 v230, 1.0, v230
	v_add_f32_e32 v231, 1.0, v231
	v_rcp_f32_e32 v230, v230
	v_rcp_f32_e32 v231, v231
	v_mul_f32_e32 v234, v94, v230
	v_mul_f32_e32 v235, v95, v231
	v_pk_mul_f32 v[234:235], v[234:235], v[90:91]
	v_cvt_pk_bf16_f32 v90, v234, v235
	v_pk_mul_f32 v[230:231], v[96:97], s[98:99]
	v_exp_f32_e32 v230, v230
	v_exp_f32_e32 v231, v231
	v_add_f32_e32 v230, 1.0, v230
	v_add_f32_e32 v231, 1.0, v231
	v_rcp_f32_e32 v230, v230
	v_rcp_f32_e32 v231, v231
	v_mul_f32_e32 v236, v96, v230
	v_mul_f32_e32 v237, v97, v231
	v_pk_mul_f32 v[236:237], v[236:237], v[92:93]
	v_cvt_pk_bf16_f32 v91, v236, v237
	v_pk_mul_f32 v[230:231], v[86:87], s[98:99]
	v_exp_f32_e32 v230, v230
	v_exp_f32_e32 v231, v231
	v_add_f32_e32 v230, 1.0, v230
	v_add_f32_e32 v231, 1.0, v231
	v_rcp_f32_e32 v230, v230
	v_rcp_f32_e32 v231, v231
	v_mul_f32_e32 v238, v86, v230
	v_mul_f32_e32 v239, v87, v231
	v_pk_mul_f32 v[238:239], v[238:239], v[82:83]
	v_cvt_pk_bf16_f32 v92, v238, v239
	v_pk_mul_f32 v[230:231], v[88:89], s[98:99]
	v_exp_f32_e32 v230, v230
	v_exp_f32_e32 v231, v231
	v_add_f32_e32 v230, 1.0, v230
	v_add_f32_e32 v231, 1.0, v231
	v_rcp_f32_e32 v230, v230
	v_rcp_f32_e32 v231, v231
	v_mul_f32_e32 v240, v88, v230
	v_mul_f32_e32 v241, v89, v231
	v_pk_mul_f32 v[240:241], v[240:241], v[84:85]
	v_cvt_pk_bf16_f32 v93, v240, v241
	v_or_b32_e32 v82, 32, v154
	v_mad_i64_i32 v[82:83], s[52:53], v82, s64, v[114:115]
	v_lshl_add_u64 v[82:83], v[82:83], 0, v[116:117]
	global_store_dwordx4 v[82:83], v[90:93], off
	v_pk_mul_f32 v[230:231], v[78:79], s[98:99]
	v_exp_f32_e32 v230, v230
	v_exp_f32_e32 v231, v231
	v_add_f32_e32 v230, 1.0, v230
	v_add_f32_e32 v231, 1.0, v231
	v_rcp_f32_e32 v230, v230
	v_rcp_f32_e32 v231, v231
	v_mul_f32_e32 v234, v78, v230
	v_mul_f32_e32 v235, v79, v231
	v_pk_mul_f32 v[234:235], v[234:235], v[74:75]
	v_cvt_pk_bf16_f32 v74, v234, v235
	v_pk_mul_f32 v[230:231], v[80:81], s[98:99]
	v_exp_f32_e32 v230, v230
	v_exp_f32_e32 v231, v231
	v_add_f32_e32 v230, 1.0, v230
	v_add_f32_e32 v231, 1.0, v231
	v_rcp_f32_e32 v230, v230
	v_rcp_f32_e32 v231, v231
	v_mul_f32_e32 v236, v80, v230
	v_mul_f32_e32 v237, v81, v231
	v_pk_mul_f32 v[236:237], v[236:237], v[76:77]
	v_cvt_pk_bf16_f32 v75, v236, v237
	v_pk_mul_f32 v[230:231], v[70:71], s[98:99]
	v_exp_f32_e32 v230, v230
	v_exp_f32_e32 v231, v231
	v_add_f32_e32 v230, 1.0, v230
	v_add_f32_e32 v231, 1.0, v231
	v_rcp_f32_e32 v230, v230
	v_rcp_f32_e32 v231, v231
	v_mul_f32_e32 v238, v70, v230
	v_mul_f32_e32 v239, v71, v231
	v_pk_mul_f32 v[238:239], v[238:239], v[66:67]
	v_cvt_pk_bf16_f32 v76, v238, v239
	v_pk_mul_f32 v[230:231], v[72:73], s[98:99]
	v_exp_f32_e32 v230, v230
	v_exp_f32_e32 v231, v231
	v_add_f32_e32 v230, 1.0, v230
	v_add_f32_e32 v231, 1.0, v231
	v_rcp_f32_e32 v230, v230
	v_rcp_f32_e32 v231, v231
	v_mul_f32_e32 v240, v72, v230
	v_mul_f32_e32 v241, v73, v231
	v_pk_mul_f32 v[240:241], v[240:241], v[68:69]
	v_cvt_pk_bf16_f32 v77, v240, v241
	v_or_b32_e32 v66, 48, v154
	v_mad_i64_i32 v[66:67], s[52:53], v66, s64, v[114:115]
	v_lshl_add_u64 v[66:67], v[66:67], 0, v[116:117]
	global_store_dwordx4 v[66:67], v[74:77], off
	v_pk_mul_f32 v[230:231], v[62:63], s[98:99]
	v_exp_f32_e32 v230, v230
	v_exp_f32_e32 v231, v231
	v_add_f32_e32 v230, 1.0, v230
	v_add_f32_e32 v231, 1.0, v231
	v_rcp_f32_e32 v230, v230
	v_rcp_f32_e32 v231, v231
	v_mul_f32_e32 v234, v62, v230
	v_mul_f32_e32 v235, v63, v231
	v_pk_mul_f32 v[234:235], v[234:235], v[58:59]
	v_cvt_pk_bf16_f32 v58, v234, v235
	v_pk_mul_f32 v[230:231], v[64:65], s[98:99]
	v_exp_f32_e32 v230, v230
	v_exp_f32_e32 v231, v231
	v_add_f32_e32 v230, 1.0, v230
	v_add_f32_e32 v231, 1.0, v231
	v_rcp_f32_e32 v230, v230
	v_rcp_f32_e32 v231, v231
	v_mul_f32_e32 v236, v64, v230
	v_mul_f32_e32 v237, v65, v231
	v_pk_mul_f32 v[236:237], v[236:237], v[60:61]
	v_cvt_pk_bf16_f32 v59, v236, v237
	v_pk_mul_f32 v[230:231], v[54:55], s[98:99]
	v_exp_f32_e32 v230, v230
	v_exp_f32_e32 v231, v231
	v_add_f32_e32 v230, 1.0, v230
	v_add_f32_e32 v231, 1.0, v231
	v_rcp_f32_e32 v230, v230
	v_rcp_f32_e32 v231, v231
	v_mul_f32_e32 v238, v54, v230
	v_mul_f32_e32 v239, v55, v231
	v_pk_mul_f32 v[238:239], v[238:239], v[50:51]
	v_cvt_pk_bf16_f32 v60, v238, v239
	v_pk_mul_f32 v[230:231], v[56:57], s[98:99]
	v_exp_f32_e32 v230, v230
	v_exp_f32_e32 v231, v231
	v_add_f32_e32 v230, 1.0, v230
	v_add_f32_e32 v231, 1.0, v231
	v_rcp_f32_e32 v230, v230
	v_rcp_f32_e32 v231, v231
	v_mul_f32_e32 v240, v56, v230
	v_mul_f32_e32 v241, v57, v231
	v_pk_mul_f32 v[240:241], v[240:241], v[52:53]
	v_add_u32_e32 v66, 0x80, v154
	v_cvt_pk_bf16_f32 v61, v240, v241
	v_mad_i64_i32 v[50:51], s[52:53], v66, s64, v[114:115]
	v_lshl_add_u64 v[50:51], v[50:51], 0, v[116:117]
	global_store_dwordx4 v[50:51], v[58:61], off
	v_pk_mul_f32 v[230:231], v[46:47], s[98:99]
	v_exp_f32_e32 v230, v230
	v_exp_f32_e32 v231, v231
	v_add_f32_e32 v230, 1.0, v230
	v_add_f32_e32 v231, 1.0, v231
	v_rcp_f32_e32 v230, v230
	v_rcp_f32_e32 v231, v231
	v_mul_f32_e32 v234, v46, v230
	v_mul_f32_e32 v235, v47, v231
	v_pk_mul_f32 v[234:235], v[234:235], v[42:43]
	v_cvt_pk_bf16_f32 v42, v234, v235
	v_pk_mul_f32 v[230:231], v[48:49], s[98:99]
	v_exp_f32_e32 v230, v230
	v_exp_f32_e32 v231, v231
	v_add_f32_e32 v230, 1.0, v230
	v_add_f32_e32 v231, 1.0, v231
	v_rcp_f32_e32 v230, v230
	v_rcp_f32_e32 v231, v231
	v_mul_f32_e32 v236, v48, v230
	v_mul_f32_e32 v237, v49, v231
	v_pk_mul_f32 v[236:237], v[236:237], v[44:45]
	v_cvt_pk_bf16_f32 v43, v236, v237
	v_pk_mul_f32 v[230:231], v[38:39], s[98:99]
	v_exp_f32_e32 v230, v230
	v_exp_f32_e32 v231, v231
	v_add_f32_e32 v230, 1.0, v230
	v_add_f32_e32 v231, 1.0, v231
	v_rcp_f32_e32 v230, v230
	v_rcp_f32_e32 v231, v231
	v_mul_f32_e32 v238, v38, v230
	v_mul_f32_e32 v239, v39, v231
	v_pk_mul_f32 v[238:239], v[238:239], v[34:35]
	v_cvt_pk_bf16_f32 v44, v238, v239
	v_pk_mul_f32 v[230:231], v[40:41], s[98:99]
	v_exp_f32_e32 v230, v230
	v_exp_f32_e32 v231, v231
	v_add_f32_e32 v230, 1.0, v230
	v_add_f32_e32 v231, 1.0, v231
	v_rcp_f32_e32 v230, v230
	v_rcp_f32_e32 v231, v231
	v_mul_f32_e32 v240, v40, v230
	v_mul_f32_e32 v241, v41, v231
	v_pk_mul_f32 v[240:241], v[240:241], v[36:37]
	v_cvt_pk_bf16_f32 v45, v240, v241
	v_add_u32_e32 v34, 0x90, v154
	v_mad_i64_i32 v[34:35], s[52:53], v34, s64, v[114:115]
	v_lshl_add_u64 v[34:35], v[34:35], 0, v[116:117]
	global_store_dwordx4 v[34:35], v[42:45], off
	v_pk_mul_f32 v[230:231], v[30:31], s[98:99]
	v_exp_f32_e32 v230, v230
	v_exp_f32_e32 v231, v231
	v_add_f32_e32 v230, 1.0, v230
	v_add_f32_e32 v231, 1.0, v231
	v_rcp_f32_e32 v230, v230
	v_rcp_f32_e32 v231, v231
	v_mul_f32_e32 v234, v30, v230
	v_mul_f32_e32 v235, v31, v231
	v_pk_mul_f32 v[234:235], v[234:235], v[26:27]
	v_cvt_pk_bf16_f32 v26, v234, v235
	v_pk_mul_f32 v[230:231], v[32:33], s[98:99]
	v_exp_f32_e32 v230, v230
	v_exp_f32_e32 v231, v231
	v_add_f32_e32 v230, 1.0, v230
	v_add_f32_e32 v231, 1.0, v231
	v_rcp_f32_e32 v230, v230
	v_rcp_f32_e32 v231, v231
	v_mul_f32_e32 v236, v32, v230
	v_mul_f32_e32 v237, v33, v231
	v_pk_mul_f32 v[236:237], v[236:237], v[28:29]
	v_cvt_pk_bf16_f32 v27, v236, v237
	v_pk_mul_f32 v[230:231], v[22:23], s[98:99]
	v_exp_f32_e32 v230, v230
	v_exp_f32_e32 v231, v231
	v_add_f32_e32 v230, 1.0, v230
	v_add_f32_e32 v231, 1.0, v231
	v_rcp_f32_e32 v230, v230
	v_rcp_f32_e32 v231, v231
	v_mul_f32_e32 v238, v22, v230
	v_mul_f32_e32 v239, v23, v231
	v_pk_mul_f32 v[238:239], v[238:239], v[18:19]
	v_cvt_pk_bf16_f32 v28, v238, v239
	v_pk_mul_f32 v[230:231], v[24:25], s[98:99]
	v_exp_f32_e32 v230, v230
	v_exp_f32_e32 v231, v231
	v_add_f32_e32 v230, 1.0, v230
	v_add_f32_e32 v231, 1.0, v231
	v_rcp_f32_e32 v230, v230
	v_rcp_f32_e32 v231, v231
	v_mul_f32_e32 v240, v24, v230
	v_mul_f32_e32 v241, v25, v231
	v_pk_mul_f32 v[240:241], v[240:241], v[20:21]
	v_cvt_pk_bf16_f32 v29, v240, v241
	v_add_u32_e32 v18, 0xa0, v154
	v_mad_i64_i32 v[18:19], s[52:53], v18, s64, v[114:115]
	v_lshl_add_u64 v[18:19], v[18:19], 0, v[116:117]
	global_store_dwordx4 v[18:19], v[26:29], off
	v_pk_mul_f32 v[230:231], v[14:15], s[98:99]
	v_exp_f32_e32 v230, v230
	v_exp_f32_e32 v231, v231
	v_add_f32_e32 v230, 1.0, v230
	v_add_f32_e32 v231, 1.0, v231
	v_rcp_f32_e32 v230, v230
	v_rcp_f32_e32 v231, v231
	v_mul_f32_e32 v234, v14, v230
	v_mul_f32_e32 v235, v15, v231
	v_pk_mul_f32 v[234:235], v[234:235], v[10:11]
	v_cvt_pk_bf16_f32 v10, v234, v235
	v_pk_mul_f32 v[230:231], v[16:17], s[98:99]
	v_exp_f32_e32 v230, v230
	v_exp_f32_e32 v231, v231
	v_add_f32_e32 v230, 1.0, v230
	v_add_f32_e32 v231, 1.0, v231
	v_rcp_f32_e32 v230, v230
	v_rcp_f32_e32 v231, v231
	v_mul_f32_e32 v236, v16, v230
	v_mul_f32_e32 v237, v17, v231
	v_pk_mul_f32 v[236:237], v[236:237], v[12:13]
	v_cvt_pk_bf16_f32 v11, v236, v237
	v_pk_mul_f32 v[230:231], v[6:7], s[98:99]
	v_exp_f32_e32 v230, v230
	v_exp_f32_e32 v231, v231
	v_add_f32_e32 v230, 1.0, v230
	v_add_f32_e32 v231, 1.0, v231
	v_rcp_f32_e32 v230, v230
	v_rcp_f32_e32 v231, v231
	v_mul_f32_e32 v238, v6, v230
	v_mul_f32_e32 v239, v7, v231
	v_pk_mul_f32 v[238:239], v[238:239], v[2:3]
	v_cvt_pk_bf16_f32 v12, v238, v239
	v_pk_mul_f32 v[230:231], v[8:9], s[98:99]
	v_exp_f32_e32 v230, v230
	v_exp_f32_e32 v231, v231
	v_add_f32_e32 v230, 1.0, v230
	v_add_f32_e32 v231, 1.0, v231
	v_rcp_f32_e32 v230, v230
	v_rcp_f32_e32 v231, v231
	v_mul_f32_e32 v240, v8, v230
	v_mul_f32_e32 v241, v9, v231
	v_pk_mul_f32 v[240:241], v[240:241], v[4:5]
	v_cvt_pk_bf16_f32 v13, v240, v241
	v_add_u32_e32 v2, 0xb0, v154
	v_mad_i64_i32 v[2:3], s[52:53], v2, s64, v[114:115]
	v_lshl_add_u64 v[2:3], v[2:3], 0, v[116:117]
	s_andn2_b64 vcc, exec, s[46:47]
	s_mov_b64 s[46:47], -1
	global_store_dwordx4 v[2:3], v[10:13], off
	s_cbranch_vccnz .LBB0_852
	s_andn2_b64 vcc, exec, s[6:7]
	s_cbranch_vccnz .LBB0_851
	s_barrier
	s_branch .LBB0_851

.LBB0_3149:
	s_mov_b32 s98, 0xbfb8aa3b
	s_mov_b32 s99, 0xbfb8aa3b
	s_lshl_b32 s5, s16, 7
	s_or_b32 s5, s36, s5
	v_or_b32_e32 v130, s5, v142
	v_add_u32_e32 v132, 0x4000, v1
	v_pk_mul_f32 v[230:231], v[126:127], s[98:99]
	v_exp_f32_e32 v230, v230
	v_exp_f32_e32 v231, v231
	v_add_f32_e32 v230, 1.0, v230
	v_add_f32_e32 v231, 1.0, v231
	v_rcp_f32_e32 v230, v230
	v_rcp_f32_e32 v231, v231
	v_mul_f32_e32 v234, v126, v230
	v_mul_f32_e32 v235, v127, v231
	v_pk_mul_f32 v[234:235], v[234:235], v[122:123]
	v_cvt_pk_bf16_f32 v122, v234, v235
	v_pk_mul_f32 v[230:231], v[128:129], s[98:99]
	v_exp_f32_e32 v230, v230
	v_exp_f32_e32 v231, v231
	v_add_f32_e32 v230, 1.0, v230
	v_add_f32_e32 v231, 1.0, v231
	v_rcp_f32_e32 v230, v230
	v_rcp_f32_e32 v231, v231
	v_mul_f32_e32 v236, v128, v230
	v_mul_f32_e32 v237, v129, v231
	v_pk_mul_f32 v[236:237], v[236:237], v[124:125]
	v_cvt_pk_bf16_f32 v123, v236, v237
	v_pk_mul_f32 v[230:231], v[118:119], s[98:99]
	v_exp_f32_e32 v230, v230
	v_exp_f32_e32 v231, v231
	v_add_f32_e32 v230, 1.0, v230
	v_add_f32_e32 v231, 1.0, v231
	v_rcp_f32_e32 v230, v230
	v_rcp_f32_e32 v231, v231
	v_mul_f32_e32 v238, v118, v230
	v_mul_f32_e32 v239, v119, v231
	v_pk_mul_f32 v[238:239], v[238:239], v[114:115]
	v_cvt_pk_bf16_f32 v124, v238, v239
	v_pk_mul_f32 v[230:231], v[120:121], s[98:99]
	v_exp_f32_e32 v230, v230
	v_exp_f32_e32 v231, v231
	v_add_f32_e32 v230, 1.0, v230
	v_add_f32_e32 v231, 1.0, v231
	v_rcp_f32_e32 v230, v230
	v_rcp_f32_e32 v231, v231
	v_mul_f32_e32 v240, v120, v230
	v_mul_f32_e32 v241, v121, v231
	v_pk_mul_f32 v[240:241], v[240:241], v[116:117]
	v_cvt_pk_bf16_f32 v125, v240, v241
	v_ashrrev_i32_e32 v131, 31, v130
	s_movk_i32 s5, 0x1600
	v_mov_b64_e32 v[114:115], s[22:23]
	v_mad_i64_i32 v[118:119], s[8:9], v132, s5, v[114:115]
	v_lshlrev_b64 v[116:117], 1, v[130:131]
	v_lshl_add_u64 v[118:119], v[118:119], 0, v[116:117]
	global_store_dwordx4 v[118:119], v[122:125], off
	s_nop 1
	v_pk_mul_f32 v[230:231], v[110:111], s[98:99]
	v_exp_f32_e32 v230, v230
	v_exp_f32_e32 v231, v231
	v_add_f32_e32 v230, 1.0, v230
	v_add_f32_e32 v231, 1.0, v231
	v_rcp_f32_e32 v230, v230
	v_rcp_f32_e32 v231, v231
	v_mul_f32_e32 v234, v110, v230
	v_mul_f32_e32 v235, v111, v231
	v_pk_mul_f32 v[234:235], v[234:235], v[106:107]
	v_cvt_pk_bf16_f32 v106, v234, v235
	v_pk_mul_f32 v[230:231], v[112:113], s[98:99]
	v_exp_f32_e32 v230, v230
	v_exp_f32_e32 v231, v231
	v_add_f32_e32 v230, 1.0, v230
	v_add_f32_e32 v231, 1.0, v231
	v_rcp_f32_e32 v230, v230
	v_rcp_f32_e32 v231, v231
	v_mul_f32_e32 v236, v112, v230
	v_mul_f32_e32 v237, v113, v231
	v_pk_mul_f32 v[236:237], v[236:237], v[108:109]
	v_cvt_pk_bf16_f32 v107, v236, v237
	v_pk_mul_f32 v[230:231], v[102:103], s[98:99]
	v_exp_f32_e32 v230, v230
	v_exp_f32_e32 v231, v231
	v_add_f32_e32 v230, 1.0, v230
	v_add_f32_e32 v231, 1.0, v231
	v_rcp_f32_e32 v230, v230
	v_rcp_f32_e32 v231, v231
	v_mul_f32_e32 v238, v102, v230
	v_mul_f32_e32 v239, v103, v231
	v_pk_mul_f32 v[238:239], v[238:239], v[98:99]
	v_cvt_pk_bf16_f32 v108, v238, v239
	v_pk_mul_f32 v[230:231], v[104:105], s[98:99]
	v_exp_f32_e32 v230, v230
	v_exp_f32_e32 v231, v231
	v_add_f32_e32 v230, 1.0, v230
	v_add_f32_e32 v231, 1.0, v231
	v_rcp_f32_e32 v230, v230
	v_rcp_f32_e32 v231, v231
	v_mul_f32_e32 v240, v104, v230
	v_mul_f32_e32 v241, v105, v231
	v_pk_mul_f32 v[240:241], v[240:241], v[100:101]
	v_cvt_pk_bf16_f32 v109, v240, v241
	v_add_u32_e32 v98, 0x4010, v1
	v_mad_i64_i32 v[98:99], s[8:9], v98, s5, v[114:115]
	v_lshl_add_u64 v[98:99], v[98:99], 0, v[116:117]
	global_store_dwordx4 v[98:99], v[106:109], off
	v_pk_mul_f32 v[230:231], v[94:95], s[98:99]
	v_exp_f32_e32 v230, v230
	v_exp_f32_e32 v231, v231
	v_add_f32_e32 v230, 1.0, v230
	v_add_f32_e32 v231, 1.0, v231
	v_rcp_f32_e32 v230, v230
	v_rcp_f32_e32 v231, v231
	v_mul_f32_e32 v234, v94, v230
	v_mul_f32_e32 v235, v95, v231
	v_pk_mul_f32 v[234:235], v[234:235], v[90:91]
	v_cvt_pk_bf16_f32 v90, v234, v235
	v_pk_mul_f32 v[230:231], v[96:97], s[98:99]
	v_exp_f32_e32 v230, v230
	v_exp_f32_e32 v231, v231
	v_add_f32_e32 v230, 1.0, v230
	v_add_f32_e32 v231, 1.0, v231
	v_rcp_f32_e32 v230, v230
	v_rcp_f32_e32 v231, v231
	v_mul_f32_e32 v236, v96, v230
	v_mul_f32_e32 v237, v97, v231
	v_pk_mul_f32 v[236:237], v[236:237], v[92:93]
	v_cvt_pk_bf16_f32 v91, v236, v237
	v_pk_mul_f32 v[230:231], v[86:87], s[98:99]
	v_exp_f32_e32 v230, v230
	v_exp_f32_e32 v231, v231
	v_add_f32_e32 v230, 1.0, v230
	v_add_f32_e32 v231, 1.0, v231
	v_rcp_f32_e32 v230, v230
	v_rcp_f32_e32 v231, v231
	v_mul_f32_e32 v238, v86, v230
	v_mul_f32_e32 v239, v87, v231
	v_pk_mul_f32 v[238:239], v[238:239], v[82:83]
	v_cvt_pk_bf16_f32 v92, v238, v239
	v_pk_mul_f32 v[230:231], v[88:89], s[98:99]
	v_exp_f32_e32 v230, v230
	v_exp_f32_e32 v231, v231
	v_add_f32_e32 v230, 1.0, v230
	v_add_f32_e32 v231, 1.0, v231
	v_rcp_f32_e32 v230, v230
	v_rcp_f32_e32 v231, v231
	v_mul_f32_e32 v240, v88, v230
	v_mul_f32_e32 v241, v89, v231
	v_pk_mul_f32 v[240:241], v[240:241], v[84:85]
	v_cvt_pk_bf16_f32 v93, v240, v241
	v_add_u32_e32 v82, 0x4020, v1
	v_mad_i64_i32 v[82:83], s[8:9], v82, s5, v[114:115]
	v_lshl_add_u64 v[82:83], v[82:83], 0, v[116:117]
	global_store_dwordx4 v[82:83], v[90:93], off
	v_pk_mul_f32 v[230:231], v[78:79], s[98:99]
	v_exp_f32_e32 v230, v230
	v_exp_f32_e32 v231, v231
	v_add_f32_e32 v230, 1.0, v230
	v_add_f32_e32 v231, 1.0, v231
	v_rcp_f32_e32 v230, v230
	v_rcp_f32_e32 v231, v231
	v_mul_f32_e32 v234, v78, v230
	v_mul_f32_e32 v235, v79, v231
	v_pk_mul_f32 v[234:235], v[234:235], v[74:75]
	v_cvt_pk_bf16_f32 v74, v234, v235
	v_pk_mul_f32 v[230:231], v[80:81], s[98:99]
	v_exp_f32_e32 v230, v230
	v_exp_f32_e32 v231, v231
	v_add_f32_e32 v230, 1.0, v230
	v_add_f32_e32 v231, 1.0, v231
	v_rcp_f32_e32 v230, v230
	v_rcp_f32_e32 v231, v231
	v_mul_f32_e32 v236, v80, v230
	v_mul_f32_e32 v237, v81, v231
	v_pk_mul_f32 v[236:237], v[236:237], v[76:77]
	v_cvt_pk_bf16_f32 v75, v236, v237
	v_pk_mul_f32 v[230:231], v[70:71], s[98:99]
	v_exp_f32_e32 v230, v230
	v_exp_f32_e32 v231, v231
	v_add_f32_e32 v230, 1.0, v230
	v_add_f32_e32 v231, 1.0, v231
	v_rcp_f32_e32 v230, v230
	v_rcp_f32_e32 v231, v231
	v_mul_f32_e32 v238, v70, v230
	v_mul_f32_e32 v239, v71, v231
	v_pk_mul_f32 v[238:239], v[238:239], v[66:67]
	v_cvt_pk_bf16_f32 v76, v238, v239
	v_pk_mul_f32 v[230:231], v[72:73], s[98:99]
	v_exp_f32_e32 v230, v230
	v_exp_f32_e32 v231, v231
	v_add_f32_e32 v230, 1.0, v230
	v_add_f32_e32 v231, 1.0, v231
	v_rcp_f32_e32 v230, v230
	v_rcp_f32_e32 v231, v231
	v_mul_f32_e32 v240, v72, v230
	v_mul_f32_e32 v241, v73, v231
	v_pk_mul_f32 v[240:241], v[240:241], v[68:69]
	v_cvt_pk_bf16_f32 v77, v240, v241
	v_add_u32_e32 v66, 0x4030, v1
	v_mad_i64_i32 v[66:67], s[8:9], v66, s5, v[114:115]
	v_lshl_add_u64 v[66:67], v[66:67], 0, v[116:117]
	global_store_dwordx4 v[66:67], v[74:77], off
	v_pk_mul_f32 v[230:231], v[62:63], s[98:99]
	v_exp_f32_e32 v230, v230
	v_exp_f32_e32 v231, v231
	v_add_f32_e32 v230, 1.0, v230
	v_add_f32_e32 v231, 1.0, v231
	v_rcp_f32_e32 v230, v230
	v_rcp_f32_e32 v231, v231
	v_mul_f32_e32 v234, v62, v230
	v_mul_f32_e32 v235, v63, v231
	v_pk_mul_f32 v[234:235], v[234:235], v[58:59]
	v_cvt_pk_bf16_f32 v58, v234, v235
	v_pk_mul_f32 v[230:231], v[64:65], s[98:99]
	v_exp_f32_e32 v230, v230
	v_exp_f32_e32 v231, v231
	v_add_f32_e32 v230, 1.0, v230
	v_add_f32_e32 v231, 1.0, v231
	v_rcp_f32_e32 v230, v230
	v_rcp_f32_e32 v231, v231
	v_mul_f32_e32 v236, v64, v230
	v_mul_f32_e32 v237, v65, v231
	v_pk_mul_f32 v[236:237], v[236:237], v[60:61]
	v_cvt_pk_bf16_f32 v59, v236, v237
	v_pk_mul_f32 v[230:231], v[54:55], s[98:99]
	v_exp_f32_e32 v230, v230
	v_exp_f32_e32 v231, v231
	v_add_f32_e32 v230, 1.0, v230
	v_add_f32_e32 v231, 1.0, v231
	v_rcp_f32_e32 v230, v230
	v_rcp_f32_e32 v231, v231
	v_mul_f32_e32 v238, v54, v230
	v_mul_f32_e32 v239, v55, v231
	v_pk_mul_f32 v[238:239], v[238:239], v[50:51]
	v_cvt_pk_bf16_f32 v60, v238, v239
	v_pk_mul_f32 v[230:231], v[56:57], s[98:99]
	v_exp_f32_e32 v230, v230
	v_exp_f32_e32 v231, v231
	v_add_f32_e32 v230, 1.0, v230
	v_add_f32_e32 v231, 1.0, v231
	v_rcp_f32_e32 v230, v230
	v_rcp_f32_e32 v231, v231
	v_mul_f32_e32 v240, v56, v230
	v_mul_f32_e32 v241, v57, v231
	v_pk_mul_f32 v[240:241], v[240:241], v[52:53]
	v_add_u32_e32 v66, 0x4080, v1
	v_cvt_pk_bf16_f32 v61, v240, v241
	v_mad_i64_i32 v[50:51], s[8:9], v66, s5, v[114:115]
	v_lshl_add_u64 v[50:51], v[50:51], 0, v[116:117]
	global_store_dwordx4 v[50:51], v[58:61], off
	v_pk_mul_f32 v[230:231], v[46:47], s[98:99]
	v_exp_f32_e32 v230, v230
	v_exp_f32_e32 v231, v231
	v_add_f32_e32 v230, 1.0, v230
	v_add_f32_e32 v231, 1.0, v231
	v_rcp_f32_e32 v230, v230
	v_rcp_f32_e32 v231, v231
	v_mul_f32_e32 v234, v46, v230
	v_mul_f32_e32 v235, v47, v231
	v_pk_mul_f32 v[234:235], v[234:235], v[42:43]
	v_cvt_pk_bf16_f32 v42, v234, v235
	v_pk_mul_f32 v[230:231], v[48:49], s[98:99]
	v_exp_f32_e32 v230, v230
	v_exp_f32_e32 v231, v231
	v_add_f32_e32 v230, 1.0, v230
	v_add_f32_e32 v231, 1.0, v231
	v_rcp_f32_e32 v230, v230
	v_rcp_f32_e32 v231, v231
	v_mul_f32_e32 v236, v48, v230
	v_mul_f32_e32 v237, v49, v231
	v_pk_mul_f32 v[236:237], v[236:237], v[44:45]
	v_cvt_pk_bf16_f32 v43, v236, v237
	v_pk_mul_f32 v[230:231], v[38:39], s[98:99]
	v_exp_f32_e32 v230, v230
	v_exp_f32_e32 v231, v231
	v_add_f32_e32 v230, 1.0, v230
	v_add_f32_e32 v231, 1.0, v231
	v_rcp_f32_e32 v230, v230
	v_rcp_f32_e32 v231, v231
	v_mul_f32_e32 v238, v38, v230
	v_mul_f32_e32 v239, v39, v231
	v_pk_mul_f32 v[238:239], v[238:239], v[34:35]
	v_cvt_pk_bf16_f32 v44, v238, v239
	v_pk_mul_f32 v[230:231], v[40:41], s[98:99]
	v_exp_f32_e32 v230, v230
	v_exp_f32_e32 v231, v231
	v_add_f32_e32 v230, 1.0, v230
	v_add_f32_e32 v231, 1.0, v231
	v_rcp_f32_e32 v230, v230
	v_rcp_f32_e32 v231, v231
	v_mul_f32_e32 v240, v40, v230
	v_mul_f32_e32 v241, v41, v231
	v_pk_mul_f32 v[240:241], v[240:241], v[36:37]
	v_cvt_pk_bf16_f32 v45, v240, v241
	v_add_u32_e32 v34, 0x4090, v1
	v_mad_i64_i32 v[34:35], s[8:9], v34, s5, v[114:115]
	v_lshl_add_u64 v[34:35], v[34:35], 0, v[116:117]
	global_store_dwordx4 v[34:35], v[42:45], off
	v_pk_mul_f32 v[230:231], v[30:31], s[98:99]
	v_exp_f32_e32 v230, v230
	v_exp_f32_e32 v231, v231
	v_add_f32_e32 v230, 1.0, v230
	v_add_f32_e32 v231, 1.0, v231
	v_rcp_f32_e32 v230, v230
	v_rcp_f32_e32 v231, v231
	v_mul_f32_e32 v234, v30, v230
	v_mul_f32_e32 v235, v31, v231
	v_pk_mul_f32 v[234:235], v[234:235], v[26:27]
	v_cvt_pk_bf16_f32 v26, v234, v235
	v_pk_mul_f32 v[230:231], v[32:33], s[98:99]
	v_exp_f32_e32 v230, v230
	v_exp_f32_e32 v231, v231
	v_add_f32_e32 v230, 1.0, v230
	v_add_f32_e32 v231, 1.0, v231
	v_rcp_f32_e32 v230, v230
	v_rcp_f32_e32 v231, v231
	v_mul_f32_e32 v236, v32, v230
	v_mul_f32_e32 v237, v33, v231
	v_pk_mul_f32 v[236:237], v[236:237], v[28:29]
	v_cvt_pk_bf16_f32 v27, v236, v237
	v_pk_mul_f32 v[230:231], v[22:23], s[98:99]
	v_exp_f32_e32 v230, v230
	v_exp_f32_e32 v231, v231
	v_add_f32_e32 v230, 1.0, v230
	v_add_f32_e32 v231, 1.0, v231
	v_rcp_f32_e32 v230, v230
	v_rcp_f32_e32 v231, v231
	v_mul_f32_e32 v238, v22, v230
	v_mul_f32_e32 v239, v23, v231
	v_pk_mul_f32 v[238:239], v[238:239], v[18:19]
	v_cvt_pk_bf16_f32 v28, v238, v239
	v_pk_mul_f32 v[230:231], v[24:25], s[98:99]
	v_exp_f32_e32 v230, v230
	v_exp_f32_e32 v231, v231
	v_add_f32_e32 v230, 1.0, v230
	v_add_f32_e32 v231, 1.0, v231
	v_rcp_f32_e32 v230, v230
	v_rcp_f32_e32 v231, v231
	v_mul_f32_e32 v240, v24, v230
	v_mul_f32_e32 v241, v25, v231
	v_pk_mul_f32 v[240:241], v[240:241], v[20:21]
	v_cvt_pk_bf16_f32 v29, v240, v241
	v_add_u32_e32 v18, 0x40a0, v1
	v_mad_i64_i32 v[18:19], s[8:9], v18, s5, v[114:115]
	v_lshl_add_u64 v[18:19], v[18:19], 0, v[116:117]
	global_store_dwordx4 v[18:19], v[26:29], off
	v_pk_mul_f32 v[230:231], v[14:15], s[98:99]
	v_exp_f32_e32 v230, v230
	v_exp_f32_e32 v231, v231
	v_add_f32_e32 v230, 1.0, v230
	v_add_f32_e32 v231, 1.0, v231
	v_rcp_f32_e32 v230, v230
	v_rcp_f32_e32 v231, v231
	v_mul_f32_e32 v234, v14, v230
	v_mul_f32_e32 v235, v15, v231
	v_pk_mul_f32 v[234:235], v[234:235], v[10:11]
	v_cvt_pk_bf16_f32 v10, v234, v235
	v_pk_mul_f32 v[230:231], v[16:17], s[98:99]
	v_exp_f32_e32 v230, v230
	v_exp_f32_e32 v231, v231
	v_add_f32_e32 v230, 1.0, v230
	v_add_f32_e32 v231, 1.0, v231
	v_rcp_f32_e32 v230, v230
	v_rcp_f32_e32 v231, v231
	v_mul_f32_e32 v236, v16, v230
	v_mul_f32_e32 v237, v17, v231
	v_pk_mul_f32 v[236:237], v[236:237], v[12:13]
	v_cvt_pk_bf16_f32 v11, v236, v237
	v_pk_mul_f32 v[230:231], v[6:7], s[98:99]
	v_exp_f32_e32 v230, v230
	v_exp_f32_e32 v231, v231
	v_add_f32_e32 v230, 1.0, v230
	v_add_f32_e32 v231, 1.0, v231
	v_rcp_f32_e32 v230, v230
	v_rcp_f32_e32 v231, v231
	v_mul_f32_e32 v238, v6, v230
	v_mul_f32_e32 v239, v7, v231
	v_pk_mul_f32 v[238:239], v[238:239], v[2:3]
	v_cvt_pk_bf16_f32 v12, v238, v239
	v_pk_mul_f32 v[230:231], v[8:9], s[98:99]
	v_exp_f32_e32 v230, v230
	v_exp_f32_e32 v231, v231
	v_add_f32_e32 v230, 1.0, v230
	v_add_f32_e32 v231, 1.0, v231
	v_rcp_f32_e32 v230, v230
	v_rcp_f32_e32 v231, v231
	v_mul_f32_e32 v240, v8, v230
	v_mul_f32_e32 v241, v9, v231
	v_pk_mul_f32 v[240:241], v[240:241], v[4:5]
	v_add_u32_e32 v1, 0x40b0, v1
	v_cvt_pk_bf16_f32 v13, v240, v241
	v_mad_i64_i32 v[2:3], s[8:9], v1, s5, v[114:115]
	v_lshl_add_u64 v[2:3], v[2:3], 0, v[116:117]
	global_store_dwordx4 v[2:3], v[10:13], off
	s_waitcnt vmcnt(0)
	s_barrier
	s_waitcnt vmcnt(0)
	s_waitcnt vmcnt(0) lgkmcnt(0)
	s_barrier
	s_mov_b64 s[8:9], exec
	v_readlane_b32 s10, v228, 2
	v_readlane_b32 s11, v228, 3
	s_and_b64 s[10:11], s[8:9], s[10:11]
	s_mov_b64 exec, s[10:11]
	s_cbranch_execz .LBB0_3152
	s_mov_b64 s[10:11], exec
	v_mbcnt_lo_u32_b32 v1, s10, 0
	buffer_wbl2 sc1
	s_waitcnt vmcnt(0)
	v_mbcnt_hi_u32_b32 v1, s11, v1
	v_cmp_eq_u32_e32 vcc, 0, v1
	s_and_b64 s[24:25], exec, vcc
	s_mov_b64 exec, s[24:25]
	s_cbranch_execz .LBB0_3152
	s_bcnt1_i32_b64 s5, s[10:11]
	v_mov_b32_e32 v1, 0
	v_mov_b32_e32 v2, s5
	global_atomic_add v1, v2, s[6:7]

.LBB0_3215:
	s_mov_b32 s98, 0xbfb8aa3b
	s_mov_b32 s99, 0xbfb8aa3b
	v_lshl_add_u32 v148, s48, 8, v1
	v_lshl_or_b32 v150, s49, 7, v142
	v_pk_mul_f32 v[230:231], v[126:127], s[98:99]
	v_exp_f32_e32 v230, v230
	v_exp_f32_e32 v231, v231
	v_add_f32_e32 v230, 1.0, v230
	v_add_f32_e32 v231, 1.0, v231
	v_rcp_f32_e32 v230, v230
	v_rcp_f32_e32 v231, v231
	v_mul_f32_e32 v234, v126, v230
	v_mul_f32_e32 v235, v127, v231
	v_pk_mul_f32 v[234:235], v[234:235], v[122:123]
	v_cvt_pk_bf16_f32 v122, v234, v235
	v_pk_mul_f32 v[230:231], v[128:129], s[98:99]
	v_exp_f32_e32 v230, v230
	v_exp_f32_e32 v231, v231
	v_add_f32_e32 v230, 1.0, v230
	v_add_f32_e32 v231, 1.0, v231
	v_rcp_f32_e32 v230, v230
	v_rcp_f32_e32 v231, v231
	v_mul_f32_e32 v236, v128, v230
	v_mul_f32_e32 v237, v129, v231
	v_pk_mul_f32 v[236:237], v[236:237], v[124:125]
	v_cvt_pk_bf16_f32 v123, v236, v237
	v_pk_mul_f32 v[230:231], v[118:119], s[98:99]
	v_exp_f32_e32 v230, v230
	v_exp_f32_e32 v231, v231
	v_add_f32_e32 v230, 1.0, v230
	v_add_f32_e32 v231, 1.0, v231
	v_rcp_f32_e32 v230, v230
	v_rcp_f32_e32 v231, v231
	v_mul_f32_e32 v238, v118, v230
	v_mul_f32_e32 v239, v119, v231
	v_pk_mul_f32 v[238:239], v[238:239], v[114:115]
	v_cvt_pk_bf16_f32 v124, v238, v239
	v_pk_mul_f32 v[230:231], v[120:121], s[98:99]
	v_exp_f32_e32 v230, v230
	v_exp_f32_e32 v231, v231
	v_add_f32_e32 v230, 1.0, v230
	v_add_f32_e32 v231, 1.0, v231
	v_rcp_f32_e32 v230, v230
	v_rcp_f32_e32 v231, v231
	v_mul_f32_e32 v240, v120, v230
	v_mul_f32_e32 v241, v121, v231
	v_pk_mul_f32 v[240:241], v[240:241], v[116:117]
	v_cvt_pk_bf16_f32 v125, v240, v241
	v_ashrrev_i32_e32 v151, 31, v150
	v_mov_b64_e32 v[114:115], s[22:23]
	v_mad_i64_i32 v[118:119], s[48:49], v148, s64, v[114:115]
	v_lshlrev_b64 v[116:117], 1, v[150:151]
	v_lshl_add_u64 v[118:119], v[118:119], 0, v[116:117]
	global_store_dwordx4 v[118:119], v[122:125], off
	s_nop 1
	v_pk_mul_f32 v[230:231], v[110:111], s[98:99]
	v_exp_f32_e32 v230, v230
	v_exp_f32_e32 v231, v231
	v_add_f32_e32 v230, 1.0, v230
	v_add_f32_e32 v231, 1.0, v231
	v_rcp_f32_e32 v230, v230
	v_rcp_f32_e32 v231, v231
	v_mul_f32_e32 v234, v110, v230
	v_mul_f32_e32 v235, v111, v231
	v_pk_mul_f32 v[234:235], v[234:235], v[106:107]
	v_cvt_pk_bf16_f32 v106, v234, v235
	v_pk_mul_f32 v[230:231], v[112:113], s[98:99]
	v_exp_f32_e32 v230, v230
	v_exp_f32_e32 v231, v231
	v_add_f32_e32 v230, 1.0, v230
	v_add_f32_e32 v231, 1.0, v231
	v_rcp_f32_e32 v230, v230
	v_rcp_f32_e32 v231, v231
	v_mul_f32_e32 v236, v112, v230
	v_mul_f32_e32 v237, v113, v231
	v_pk_mul_f32 v[236:237], v[236:237], v[108:109]
	v_cvt_pk_bf16_f32 v107, v236, v237
	v_pk_mul_f32 v[230:231], v[102:103], s[98:99]
	v_exp_f32_e32 v230, v230
	v_exp_f32_e32 v231, v231
	v_add_f32_e32 v230, 1.0, v230
	v_add_f32_e32 v231, 1.0, v231
	v_rcp_f32_e32 v230, v230
	v_rcp_f32_e32 v231, v231
	v_mul_f32_e32 v238, v102, v230
	v_mul_f32_e32 v239, v103, v231
	v_pk_mul_f32 v[238:239], v[238:239], v[98:99]
	v_cvt_pk_bf16_f32 v108, v238, v239
	v_pk_mul_f32 v[230:231], v[104:105], s[98:99]
	v_exp_f32_e32 v230, v230
	v_exp_f32_e32 v231, v231
	v_add_f32_e32 v230, 1.0, v230
	v_add_f32_e32 v231, 1.0, v231
	v_rcp_f32_e32 v230, v230
	v_rcp_f32_e32 v231, v231
	v_mul_f32_e32 v240, v104, v230
	v_mul_f32_e32 v241, v105, v231
	v_pk_mul_f32 v[240:241], v[240:241], v[100:101]
	v_cvt_pk_bf16_f32 v109, v240, v241
	v_or_b32_e32 v98, 16, v148
	v_mad_i64_i32 v[98:99], s[48:49], v98, s64, v[114:115]
	v_lshl_add_u64 v[98:99], v[98:99], 0, v[116:117]
	global_store_dwordx4 v[98:99], v[106:109], off
	v_pk_mul_f32 v[230:231], v[94:95], s[98:99]
	v_exp_f32_e32 v230, v230
	v_exp_f32_e32 v231, v231
	v_add_f32_e32 v230, 1.0, v230
	v_add_f32_e32 v231, 1.0, v231
	v_rcp_f32_e32 v230, v230
	v_rcp_f32_e32 v231, v231
	v_mul_f32_e32 v234, v94, v230
	v_mul_f32_e32 v235, v95, v231
	v_pk_mul_f32 v[234:235], v[234:235], v[90:91]
	v_cvt_pk_bf16_f32 v90, v234, v235
	v_pk_mul_f32 v[230:231], v[96:97], s[98:99]
	v_exp_f32_e32 v230, v230
	v_exp_f32_e32 v231, v231
	v_add_f32_e32 v230, 1.0, v230
	v_add_f32_e32 v231, 1.0, v231
	v_rcp_f32_e32 v230, v230
	v_rcp_f32_e32 v231, v231
	v_mul_f32_e32 v236, v96, v230
	v_mul_f32_e32 v237, v97, v231
	v_pk_mul_f32 v[236:237], v[236:237], v[92:93]
	v_cvt_pk_bf16_f32 v91, v236, v237
	v_pk_mul_f32 v[230:231], v[86:87], s[98:99]
	v_exp_f32_e32 v230, v230
	v_exp_f32_e32 v231, v231
	v_add_f32_e32 v230, 1.0, v230
	v_add_f32_e32 v231, 1.0, v231
	v_rcp_f32_e32 v230, v230
	v_rcp_f32_e32 v231, v231
	v_mul_f32_e32 v238, v86, v230
	v_mul_f32_e32 v239, v87, v231
	v_pk_mul_f32 v[238:239], v[238:239], v[82:83]
	v_cvt_pk_bf16_f32 v92, v238, v239
	v_pk_mul_f32 v[230:231], v[88:89], s[98:99]
	v_exp_f32_e32 v230, v230
	v_exp_f32_e32 v231, v231
	v_add_f32_e32 v230, 1.0, v230
	v_add_f32_e32 v231, 1.0, v231
	v_rcp_f32_e32 v230, v230
	v_rcp_f32_e32 v231, v231
	v_mul_f32_e32 v240, v88, v230
	v_mul_f32_e32 v241, v89, v231
	v_pk_mul_f32 v[240:241], v[240:241], v[84:85]
	v_cvt_pk_bf16_f32 v93, v240, v241
	v_or_b32_e32 v82, 32, v148
	v_mad_i64_i32 v[82:83], s[48:49], v82, s64, v[114:115]
	v_lshl_add_u64 v[82:83], v[82:83], 0, v[116:117]
	global_store_dwordx4 v[82:83], v[90:93], off
	v_pk_mul_f32 v[230:231], v[78:79], s[98:99]
	v_exp_f32_e32 v230, v230
	v_exp_f32_e32 v231, v231
	v_add_f32_e32 v230, 1.0, v230
	v_add_f32_e32 v231, 1.0, v231
	v_rcp_f32_e32 v230, v230
	v_rcp_f32_e32 v231, v231
	v_mul_f32_e32 v234, v78, v230
	v_mul_f32_e32 v235, v79, v231
	v_pk_mul_f32 v[234:235], v[234:235], v[74:75]
	v_cvt_pk_bf16_f32 v74, v234, v235
	v_pk_mul_f32 v[230:231], v[80:81], s[98:99]
	v_exp_f32_e32 v230, v230
	v_exp_f32_e32 v231, v231
	v_add_f32_e32 v230, 1.0, v230
	v_add_f32_e32 v231, 1.0, v231
	v_rcp_f32_e32 v230, v230
	v_rcp_f32_e32 v231, v231
	v_mul_f32_e32 v236, v80, v230
	v_mul_f32_e32 v237, v81, v231
	v_pk_mul_f32 v[236:237], v[236:237], v[76:77]
	v_cvt_pk_bf16_f32 v75, v236, v237
	v_pk_mul_f32 v[230:231], v[70:71], s[98:99]
	v_exp_f32_e32 v230, v230
	v_exp_f32_e32 v231, v231
	v_add_f32_e32 v230, 1.0, v230
	v_add_f32_e32 v231, 1.0, v231
	v_rcp_f32_e32 v230, v230
	v_rcp_f32_e32 v231, v231
	v_mul_f32_e32 v238, v70, v230
	v_mul_f32_e32 v239, v71, v231
	v_pk_mul_f32 v[238:239], v[238:239], v[66:67]
	v_cvt_pk_bf16_f32 v76, v238, v239
	v_pk_mul_f32 v[230:231], v[72:73], s[98:99]
	v_exp_f32_e32 v230, v230
	v_exp_f32_e32 v231, v231
	v_add_f32_e32 v230, 1.0, v230
	v_add_f32_e32 v231, 1.0, v231
	v_rcp_f32_e32 v230, v230
	v_rcp_f32_e32 v231, v231
	v_mul_f32_e32 v240, v72, v230
	v_mul_f32_e32 v241, v73, v231
	v_pk_mul_f32 v[240:241], v[240:241], v[68:69]
	v_cvt_pk_bf16_f32 v77, v240, v241
	v_or_b32_e32 v66, 48, v148
	v_mad_i64_i32 v[66:67], s[48:49], v66, s64, v[114:115]
	v_lshl_add_u64 v[66:67], v[66:67], 0, v[116:117]
	global_store_dwordx4 v[66:67], v[74:77], off
	v_pk_mul_f32 v[230:231], v[62:63], s[98:99]
	v_exp_f32_e32 v230, v230
	v_exp_f32_e32 v231, v231
	v_add_f32_e32 v230, 1.0, v230
	v_add_f32_e32 v231, 1.0, v231
	v_rcp_f32_e32 v230, v230
	v_rcp_f32_e32 v231, v231
	v_mul_f32_e32 v234, v62, v230
	v_mul_f32_e32 v235, v63, v231
	v_pk_mul_f32 v[234:235], v[234:235], v[58:59]
	v_cvt_pk_bf16_f32 v58, v234, v235
	v_pk_mul_f32 v[230:231], v[64:65], s[98:99]
	v_exp_f32_e32 v230, v230
	v_exp_f32_e32 v231, v231
	v_add_f32_e32 v230, 1.0, v230
	v_add_f32_e32 v231, 1.0, v231
	v_rcp_f32_e32 v230, v230
	v_rcp_f32_e32 v231, v231
	v_mul_f32_e32 v236, v64, v230
	v_mul_f32_e32 v237, v65, v231
	v_pk_mul_f32 v[236:237], v[236:237], v[60:61]
	v_cvt_pk_bf16_f32 v59, v236, v237
	v_pk_mul_f32 v[230:231], v[54:55], s[98:99]
	v_exp_f32_e32 v230, v230
	v_exp_f32_e32 v231, v231
	v_add_f32_e32 v230, 1.0, v230
	v_add_f32_e32 v231, 1.0, v231
	v_rcp_f32_e32 v230, v230
	v_rcp_f32_e32 v231, v231
	v_mul_f32_e32 v238, v54, v230
	v_mul_f32_e32 v239, v55, v231
	v_pk_mul_f32 v[238:239], v[238:239], v[50:51]
	v_cvt_pk_bf16_f32 v60, v238, v239
	v_pk_mul_f32 v[230:231], v[56:57], s[98:99]
	v_exp_f32_e32 v230, v230
	v_exp_f32_e32 v231, v231
	v_add_f32_e32 v230, 1.0, v230
	v_add_f32_e32 v231, 1.0, v231
	v_rcp_f32_e32 v230, v230
	v_rcp_f32_e32 v231, v231
	v_mul_f32_e32 v240, v56, v230
	v_mul_f32_e32 v241, v57, v231
	v_pk_mul_f32 v[240:241], v[240:241], v[52:53]
	v_add_u32_e32 v66, 0x80, v148
	v_cvt_pk_bf16_f32 v61, v240, v241
	v_mad_i64_i32 v[50:51], s[48:49], v66, s64, v[114:115]
	v_lshl_add_u64 v[50:51], v[50:51], 0, v[116:117]
	global_store_dwordx4 v[50:51], v[58:61], off
	v_pk_mul_f32 v[230:231], v[46:47], s[98:99]
	v_exp_f32_e32 v230, v230
	v_exp_f32_e32 v231, v231
	v_add_f32_e32 v230, 1.0, v230
	v_add_f32_e32 v231, 1.0, v231
	v_rcp_f32_e32 v230, v230
	v_rcp_f32_e32 v231, v231
	v_mul_f32_e32 v234, v46, v230
	v_mul_f32_e32 v235, v47, v231
	v_pk_mul_f32 v[234:235], v[234:235], v[42:43]
	v_cvt_pk_bf16_f32 v42, v234, v235
	v_pk_mul_f32 v[230:231], v[48:49], s[98:99]
	v_exp_f32_e32 v230, v230
	v_exp_f32_e32 v231, v231
	v_add_f32_e32 v230, 1.0, v230
	v_add_f32_e32 v231, 1.0, v231
	v_rcp_f32_e32 v230, v230
	v_rcp_f32_e32 v231, v231
	v_mul_f32_e32 v236, v48, v230
	v_mul_f32_e32 v237, v49, v231
	v_pk_mul_f32 v[236:237], v[236:237], v[44:45]
	v_cvt_pk_bf16_f32 v43, v236, v237
	v_pk_mul_f32 v[230:231], v[38:39], s[98:99]
	v_exp_f32_e32 v230, v230
	v_exp_f32_e32 v231, v231
	v_add_f32_e32 v230, 1.0, v230
	v_add_f32_e32 v231, 1.0, v231
	v_rcp_f32_e32 v230, v230
	v_rcp_f32_e32 v231, v231
	v_mul_f32_e32 v238, v38, v230
	v_mul_f32_e32 v239, v39, v231
	v_pk_mul_f32 v[238:239], v[238:239], v[34:35]
	v_cvt_pk_bf16_f32 v44, v238, v239
	v_pk_mul_f32 v[230:231], v[40:41], s[98:99]
	v_exp_f32_e32 v230, v230
	v_exp_f32_e32 v231, v231
	v_add_f32_e32 v230, 1.0, v230
	v_add_f32_e32 v231, 1.0, v231
	v_rcp_f32_e32 v230, v230
	v_rcp_f32_e32 v231, v231
	v_mul_f32_e32 v240, v40, v230
	v_mul_f32_e32 v241, v41, v231
	v_pk_mul_f32 v[240:241], v[240:241], v[36:37]
	v_cvt_pk_bf16_f32 v45, v240, v241
	v_add_u32_e32 v34, 0x90, v148
	v_mad_i64_i32 v[34:35], s[48:49], v34, s64, v[114:115]
	v_lshl_add_u64 v[34:35], v[34:35], 0, v[116:117]
	global_store_dwordx4 v[34:35], v[42:45], off
	v_pk_mul_f32 v[230:231], v[30:31], s[98:99]
	v_exp_f32_e32 v230, v230
	v_exp_f32_e32 v231, v231
	v_add_f32_e32 v230, 1.0, v230
	v_add_f32_e32 v231, 1.0, v231
	v_rcp_f32_e32 v230, v230
	v_rcp_f32_e32 v231, v231
	v_mul_f32_e32 v234, v30, v230
	v_mul_f32_e32 v235, v31, v231
	v_pk_mul_f32 v[234:235], v[234:235], v[26:27]
	v_cvt_pk_bf16_f32 v26, v234, v235
	v_pk_mul_f32 v[230:231], v[32:33], s[98:99]
	v_exp_f32_e32 v230, v230
	v_exp_f32_e32 v231, v231
	v_add_f32_e32 v230, 1.0, v230
	v_add_f32_e32 v231, 1.0, v231
	v_rcp_f32_e32 v230, v230
	v_rcp_f32_e32 v231, v231
	v_mul_f32_e32 v236, v32, v230
	v_mul_f32_e32 v237, v33, v231
	v_pk_mul_f32 v[236:237], v[236:237], v[28:29]
	v_cvt_pk_bf16_f32 v27, v236, v237
	v_pk_mul_f32 v[230:231], v[22:23], s[98:99]
	v_exp_f32_e32 v230, v230
	v_exp_f32_e32 v231, v231
	v_add_f32_e32 v230, 1.0, v230
	v_add_f32_e32 v231, 1.0, v231
	v_rcp_f32_e32 v230, v230
	v_rcp_f32_e32 v231, v231
	v_mul_f32_e32 v238, v22, v230
	v_mul_f32_e32 v239, v23, v231
	v_pk_mul_f32 v[238:239], v[238:239], v[18:19]
	v_cvt_pk_bf16_f32 v28, v238, v239
	v_pk_mul_f32 v[230:231], v[24:25], s[98:99]
	v_exp_f32_e32 v230, v230
	v_exp_f32_e32 v231, v231
	v_add_f32_e32 v230, 1.0, v230
	v_add_f32_e32 v231, 1.0, v231
	v_rcp_f32_e32 v230, v230
	v_rcp_f32_e32 v231, v231
	v_mul_f32_e32 v240, v24, v230
	v_mul_f32_e32 v241, v25, v231
	v_pk_mul_f32 v[240:241], v[240:241], v[20:21]
	v_cvt_pk_bf16_f32 v29, v240, v241
	v_add_u32_e32 v18, 0xa0, v148
	v_mad_i64_i32 v[18:19], s[48:49], v18, s64, v[114:115]
	v_lshl_add_u64 v[18:19], v[18:19], 0, v[116:117]
	global_store_dwordx4 v[18:19], v[26:29], off
	v_pk_mul_f32 v[230:231], v[14:15], s[98:99]
	v_exp_f32_e32 v230, v230
	v_exp_f32_e32 v231, v231
	v_add_f32_e32 v230, 1.0, v230
	v_add_f32_e32 v231, 1.0, v231
	v_rcp_f32_e32 v230, v230
	v_rcp_f32_e32 v231, v231
	v_mul_f32_e32 v234, v14, v230
	v_mul_f32_e32 v235, v15, v231
	v_pk_mul_f32 v[234:235], v[234:235], v[10:11]
	v_cvt_pk_bf16_f32 v10, v234, v235
	v_pk_mul_f32 v[230:231], v[16:17], s[98:99]
	v_exp_f32_e32 v230, v230
	v_exp_f32_e32 v231, v231
	v_add_f32_e32 v230, 1.0, v230
	v_add_f32_e32 v231, 1.0, v231
	v_rcp_f32_e32 v230, v230
	v_rcp_f32_e32 v231, v231
	v_mul_f32_e32 v236, v16, v230
	v_mul_f32_e32 v237, v17, v231
	v_pk_mul_f32 v[236:237], v[236:237], v[12:13]
	v_cvt_pk_bf16_f32 v11, v236, v237
	v_pk_mul_f32 v[230:231], v[6:7], s[98:99]
	v_exp_f32_e32 v230, v230
	v_exp_f32_e32 v231, v231
	v_add_f32_e32 v230, 1.0, v230
	v_add_f32_e32 v231, 1.0, v231
	v_rcp_f32_e32 v230, v230
	v_rcp_f32_e32 v231, v231
	v_mul_f32_e32 v238, v6, v230
	v_mul_f32_e32 v239, v7, v231
	v_pk_mul_f32 v[238:239], v[238:239], v[2:3]
	v_cvt_pk_bf16_f32 v12, v238, v239
	v_pk_mul_f32 v[230:231], v[8:9], s[98:99]
	v_exp_f32_e32 v230, v230
	v_exp_f32_e32 v231, v231
	v_add_f32_e32 v230, 1.0, v230
	v_add_f32_e32 v231, 1.0, v231
	v_rcp_f32_e32 v230, v230
	v_rcp_f32_e32 v231, v231
	v_mul_f32_e32 v240, v8, v230
	v_mul_f32_e32 v241, v9, v231
	v_pk_mul_f32 v[240:241], v[240:241], v[4:5]
	v_cvt_pk_bf16_f32 v13, v240, v241
	v_add_u32_e32 v2, 0xb0, v148
	v_mad_i64_i32 v[2:3], s[48:49], v2, s64, v[114:115]
	v_lshl_add_u64 v[2:3], v[2:3], 0, v[116:117]
	s_mov_b64 s[48:49], -1
	s_and_b64 vcc, exec, s[44:45]
	global_store_dwordx4 v[2:3], v[10:13], off
	s_cbranch_vccz .LBB0_3204
	s_andn2_b64 vcc, exec, s[6:7]
	s_cbranch_vccnz .LBB0_3203
	s_barrier
	s_branch .LBB0_3203

.LBB0_3404:
	s_mov_b32 s98, 0xbfb8aa3b
	s_mov_b32 s99, 0xbfb8aa3b
	s_lshl_b32 s5, s40, 7
	s_or_b32 s5, s34, s5
	v_or_b32_e32 v134, s5, v131
	v_add_u32_e32 v136, 0x4000, v1
	v_pk_mul_f32 v[230:231], v[126:127], s[98:99]
	v_exp_f32_e32 v230, v230
	v_exp_f32_e32 v231, v231
	v_add_f32_e32 v230, 1.0, v230
	v_add_f32_e32 v231, 1.0, v231
	v_rcp_f32_e32 v230, v230
	v_rcp_f32_e32 v231, v231
	v_mul_f32_e32 v234, v126, v230
	v_mul_f32_e32 v235, v127, v231
	v_pk_mul_f32 v[234:235], v[234:235], v[122:123]
	v_cvt_pk_bf16_f32 v122, v234, v235
	v_pk_mul_f32 v[230:231], v[128:129], s[98:99]
	v_exp_f32_e32 v230, v230
	v_exp_f32_e32 v231, v231
	v_add_f32_e32 v230, 1.0, v230
	v_add_f32_e32 v231, 1.0, v231
	v_rcp_f32_e32 v230, v230
	v_rcp_f32_e32 v231, v231
	v_mul_f32_e32 v236, v128, v230
	v_mul_f32_e32 v237, v129, v231
	v_pk_mul_f32 v[236:237], v[236:237], v[124:125]
	v_cvt_pk_bf16_f32 v123, v236, v237
	v_pk_mul_f32 v[230:231], v[118:119], s[98:99]
	v_exp_f32_e32 v230, v230
	v_exp_f32_e32 v231, v231
	v_add_f32_e32 v230, 1.0, v230
	v_add_f32_e32 v231, 1.0, v231
	v_rcp_f32_e32 v230, v230
	v_rcp_f32_e32 v231, v231
	v_mul_f32_e32 v238, v118, v230
	v_mul_f32_e32 v239, v119, v231
	v_pk_mul_f32 v[238:239], v[238:239], v[114:115]
	v_cvt_pk_bf16_f32 v124, v238, v239
	v_pk_mul_f32 v[230:231], v[120:121], s[98:99]
	v_exp_f32_e32 v230, v230
	v_exp_f32_e32 v231, v231
	v_add_f32_e32 v230, 1.0, v230
	v_add_f32_e32 v231, 1.0, v231
	v_rcp_f32_e32 v230, v230
	v_rcp_f32_e32 v231, v231
	v_mul_f32_e32 v240, v120, v230
	v_mul_f32_e32 v241, v121, v231
	v_pk_mul_f32 v[240:241], v[240:241], v[116:117]
	v_cvt_pk_bf16_f32 v125, v240, v241
	v_ashrrev_i32_e32 v135, 31, v134
	s_movk_i32 s5, 0x1600
	v_mov_b64_e32 v[114:115], s[18:19]
	v_mad_i64_i32 v[118:119], s[8:9], v136, s5, v[114:115]
	v_lshlrev_b64 v[116:117], 1, v[134:135]
	v_lshl_add_u64 v[118:119], v[118:119], 0, v[116:117]
	global_store_dwordx4 v[118:119], v[122:125], off
	s_nop 1
	v_pk_mul_f32 v[230:231], v[110:111], s[98:99]
	v_exp_f32_e32 v230, v230
	v_exp_f32_e32 v231, v231
	v_add_f32_e32 v230, 1.0, v230
	v_add_f32_e32 v231, 1.0, v231
	v_rcp_f32_e32 v230, v230
	v_rcp_f32_e32 v231, v231
	v_mul_f32_e32 v234, v110, v230
	v_mul_f32_e32 v235, v111, v231
	v_pk_mul_f32 v[234:235], v[234:235], v[106:107]
	v_cvt_pk_bf16_f32 v106, v234, v235
	v_pk_mul_f32 v[230:231], v[112:113], s[98:99]
	v_exp_f32_e32 v230, v230
	v_exp_f32_e32 v231, v231
	v_add_f32_e32 v230, 1.0, v230
	v_add_f32_e32 v231, 1.0, v231
	v_rcp_f32_e32 v230, v230
	v_rcp_f32_e32 v231, v231
	v_mul_f32_e32 v236, v112, v230
	v_mul_f32_e32 v237, v113, v231
	v_pk_mul_f32 v[236:237], v[236:237], v[108:109]
	v_cvt_pk_bf16_f32 v107, v236, v237
	v_pk_mul_f32 v[230:231], v[102:103], s[98:99]
	v_exp_f32_e32 v230, v230
	v_exp_f32_e32 v231, v231
	v_add_f32_e32 v230, 1.0, v230
	v_add_f32_e32 v231, 1.0, v231
	v_rcp_f32_e32 v230, v230
	v_rcp_f32_e32 v231, v231
	v_mul_f32_e32 v238, v102, v230
	v_mul_f32_e32 v239, v103, v231
	v_pk_mul_f32 v[238:239], v[238:239], v[98:99]
	v_cvt_pk_bf16_f32 v108, v238, v239
	v_pk_mul_f32 v[230:231], v[104:105], s[98:99]
	v_exp_f32_e32 v230, v230
	v_exp_f32_e32 v231, v231
	v_add_f32_e32 v230, 1.0, v230
	v_add_f32_e32 v231, 1.0, v231
	v_rcp_f32_e32 v230, v230
	v_rcp_f32_e32 v231, v231
	v_mul_f32_e32 v240, v104, v230
	v_mul_f32_e32 v241, v105, v231
	v_pk_mul_f32 v[240:241], v[240:241], v[100:101]
	v_cvt_pk_bf16_f32 v109, v240, v241
	v_add_u32_e32 v98, 0x4010, v1
	v_mad_i64_i32 v[98:99], s[8:9], v98, s5, v[114:115]
	v_lshl_add_u64 v[98:99], v[98:99], 0, v[116:117]
	global_store_dwordx4 v[98:99], v[106:109], off
	v_pk_mul_f32 v[230:231], v[94:95], s[98:99]
	v_exp_f32_e32 v230, v230
	v_exp_f32_e32 v231, v231
	v_add_f32_e32 v230, 1.0, v230
	v_add_f32_e32 v231, 1.0, v231
	v_rcp_f32_e32 v230, v230
	v_rcp_f32_e32 v231, v231
	v_mul_f32_e32 v234, v94, v230
	v_mul_f32_e32 v235, v95, v231
	v_pk_mul_f32 v[234:235], v[234:235], v[90:91]
	v_cvt_pk_bf16_f32 v90, v234, v235
	v_pk_mul_f32 v[230:231], v[96:97], s[98:99]
	v_exp_f32_e32 v230, v230
	v_exp_f32_e32 v231, v231
	v_add_f32_e32 v230, 1.0, v230
	v_add_f32_e32 v231, 1.0, v231
	v_rcp_f32_e32 v230, v230
	v_rcp_f32_e32 v231, v231
	v_mul_f32_e32 v236, v96, v230
	v_mul_f32_e32 v237, v97, v231
	v_pk_mul_f32 v[236:237], v[236:237], v[92:93]
	v_cvt_pk_bf16_f32 v91, v236, v237
	v_pk_mul_f32 v[230:231], v[86:87], s[98:99]
	v_exp_f32_e32 v230, v230
	v_exp_f32_e32 v231, v231
	v_add_f32_e32 v230, 1.0, v230
	v_add_f32_e32 v231, 1.0, v231
	v_rcp_f32_e32 v230, v230
	v_rcp_f32_e32 v231, v231
	v_mul_f32_e32 v238, v86, v230
	v_mul_f32_e32 v239, v87, v231
	v_pk_mul_f32 v[238:239], v[238:239], v[82:83]
	v_cvt_pk_bf16_f32 v92, v238, v239
	v_pk_mul_f32 v[230:231], v[88:89], s[98:99]
	v_exp_f32_e32 v230, v230
	v_exp_f32_e32 v231, v231
	v_add_f32_e32 v230, 1.0, v230
	v_add_f32_e32 v231, 1.0, v231
	v_rcp_f32_e32 v230, v230
	v_rcp_f32_e32 v231, v231
	v_mul_f32_e32 v240, v88, v230
	v_mul_f32_e32 v241, v89, v231
	v_pk_mul_f32 v[240:241], v[240:241], v[84:85]
	v_cvt_pk_bf16_f32 v93, v240, v241
	v_add_u32_e32 v82, 0x4020, v1
	v_mad_i64_i32 v[82:83], s[8:9], v82, s5, v[114:115]
	v_lshl_add_u64 v[82:83], v[82:83], 0, v[116:117]
	global_store_dwordx4 v[82:83], v[90:93], off
	v_pk_mul_f32 v[230:231], v[78:79], s[98:99]
	v_exp_f32_e32 v230, v230
	v_exp_f32_e32 v231, v231
	v_add_f32_e32 v230, 1.0, v230
	v_add_f32_e32 v231, 1.0, v231
	v_rcp_f32_e32 v230, v230
	v_rcp_f32_e32 v231, v231
	v_mul_f32_e32 v234, v78, v230
	v_mul_f32_e32 v235, v79, v231
	v_pk_mul_f32 v[234:235], v[234:235], v[74:75]
	v_cvt_pk_bf16_f32 v74, v234, v235
	v_pk_mul_f32 v[230:231], v[80:81], s[98:99]
	v_exp_f32_e32 v230, v230
	v_exp_f32_e32 v231, v231
	v_add_f32_e32 v230, 1.0, v230
	v_add_f32_e32 v231, 1.0, v231
	v_rcp_f32_e32 v230, v230
	v_rcp_f32_e32 v231, v231
	v_mul_f32_e32 v236, v80, v230
	v_mul_f32_e32 v237, v81, v231
	v_pk_mul_f32 v[236:237], v[236:237], v[76:77]
	v_cvt_pk_bf16_f32 v75, v236, v237
	v_pk_mul_f32 v[230:231], v[70:71], s[98:99]
	v_exp_f32_e32 v230, v230
	v_exp_f32_e32 v231, v231
	v_add_f32_e32 v230, 1.0, v230
	v_add_f32_e32 v231, 1.0, v231
	v_rcp_f32_e32 v230, v230
	v_rcp_f32_e32 v231, v231
	v_mul_f32_e32 v238, v70, v230
	v_mul_f32_e32 v239, v71, v231
	v_pk_mul_f32 v[238:239], v[238:239], v[66:67]
	v_cvt_pk_bf16_f32 v76, v238, v239
	v_pk_mul_f32 v[230:231], v[72:73], s[98:99]
	v_exp_f32_e32 v230, v230
	v_exp_f32_e32 v231, v231
	v_add_f32_e32 v230, 1.0, v230
	v_add_f32_e32 v231, 1.0, v231
	v_rcp_f32_e32 v230, v230
	v_rcp_f32_e32 v231, v231
	v_mul_f32_e32 v240, v72, v230
	v_mul_f32_e32 v241, v73, v231
	v_pk_mul_f32 v[240:241], v[240:241], v[68:69]
	v_cvt_pk_bf16_f32 v77, v240, v241
	v_add_u32_e32 v66, 0x4030, v1
	v_mad_i64_i32 v[66:67], s[8:9], v66, s5, v[114:115]
	v_lshl_add_u64 v[66:67], v[66:67], 0, v[116:117]
	global_store_dwordx4 v[66:67], v[74:77], off
	v_pk_mul_f32 v[230:231], v[62:63], s[98:99]
	v_exp_f32_e32 v230, v230
	v_exp_f32_e32 v231, v231
	v_add_f32_e32 v230, 1.0, v230
	v_add_f32_e32 v231, 1.0, v231
	v_rcp_f32_e32 v230, v230
	v_rcp_f32_e32 v231, v231
	v_mul_f32_e32 v234, v62, v230
	v_mul_f32_e32 v235, v63, v231
	v_pk_mul_f32 v[234:235], v[234:235], v[58:59]
	v_cvt_pk_bf16_f32 v58, v234, v235
	v_pk_mul_f32 v[230:231], v[64:65], s[98:99]
	v_exp_f32_e32 v230, v230
	v_exp_f32_e32 v231, v231
	v_add_f32_e32 v230, 1.0, v230
	v_add_f32_e32 v231, 1.0, v231
	v_rcp_f32_e32 v230, v230
	v_rcp_f32_e32 v231, v231
	v_mul_f32_e32 v236, v64, v230
	v_mul_f32_e32 v237, v65, v231
	v_pk_mul_f32 v[236:237], v[236:237], v[60:61]
	v_cvt_pk_bf16_f32 v59, v236, v237
	v_pk_mul_f32 v[230:231], v[54:55], s[98:99]
	v_exp_f32_e32 v230, v230
	v_exp_f32_e32 v231, v231
	v_add_f32_e32 v230, 1.0, v230
	v_add_f32_e32 v231, 1.0, v231
	v_rcp_f32_e32 v230, v230
	v_rcp_f32_e32 v231, v231
	v_mul_f32_e32 v238, v54, v230
	v_mul_f32_e32 v239, v55, v231
	v_pk_mul_f32 v[238:239], v[238:239], v[50:51]
	v_cvt_pk_bf16_f32 v60, v238, v239
	v_pk_mul_f32 v[230:231], v[56:57], s[98:99]
	v_exp_f32_e32 v230, v230
	v_exp_f32_e32 v231, v231
	v_add_f32_e32 v230, 1.0, v230
	v_add_f32_e32 v231, 1.0, v231
	v_rcp_f32_e32 v230, v230
	v_rcp_f32_e32 v231, v231
	v_mul_f32_e32 v240, v56, v230
	v_mul_f32_e32 v241, v57, v231
	v_pk_mul_f32 v[240:241], v[240:241], v[52:53]
	v_add_u32_e32 v66, 0x4080, v1
	v_cvt_pk_bf16_f32 v61, v240, v241
	v_mad_i64_i32 v[50:51], s[8:9], v66, s5, v[114:115]
	v_lshl_add_u64 v[50:51], v[50:51], 0, v[116:117]
	global_store_dwordx4 v[50:51], v[58:61], off
	v_pk_mul_f32 v[230:231], v[46:47], s[98:99]
	v_exp_f32_e32 v230, v230
	v_exp_f32_e32 v231, v231
	v_add_f32_e32 v230, 1.0, v230
	v_add_f32_e32 v231, 1.0, v231
	v_rcp_f32_e32 v230, v230
	v_rcp_f32_e32 v231, v231
	v_mul_f32_e32 v234, v46, v230
	v_mul_f32_e32 v235, v47, v231
	v_pk_mul_f32 v[234:235], v[234:235], v[42:43]
	v_cvt_pk_bf16_f32 v42, v234, v235
	v_pk_mul_f32 v[230:231], v[48:49], s[98:99]
	v_exp_f32_e32 v230, v230
	v_exp_f32_e32 v231, v231
	v_add_f32_e32 v230, 1.0, v230
	v_add_f32_e32 v231, 1.0, v231
	v_rcp_f32_e32 v230, v230
	v_rcp_f32_e32 v231, v231
	v_mul_f32_e32 v236, v48, v230
	v_mul_f32_e32 v237, v49, v231
	v_pk_mul_f32 v[236:237], v[236:237], v[44:45]
	v_cvt_pk_bf16_f32 v43, v236, v237
	v_pk_mul_f32 v[230:231], v[38:39], s[98:99]
	v_exp_f32_e32 v230, v230
	v_exp_f32_e32 v231, v231
	v_add_f32_e32 v230, 1.0, v230
	v_add_f32_e32 v231, 1.0, v231
	v_rcp_f32_e32 v230, v230
	v_rcp_f32_e32 v231, v231
	v_mul_f32_e32 v238, v38, v230
	v_mul_f32_e32 v239, v39, v231
	v_pk_mul_f32 v[238:239], v[238:239], v[34:35]
	v_cvt_pk_bf16_f32 v44, v238, v239
	v_pk_mul_f32 v[230:231], v[40:41], s[98:99]
	v_exp_f32_e32 v230, v230
	v_exp_f32_e32 v231, v231
	v_add_f32_e32 v230, 1.0, v230
	v_add_f32_e32 v231, 1.0, v231
	v_rcp_f32_e32 v230, v230
	v_rcp_f32_e32 v231, v231
	v_mul_f32_e32 v240, v40, v230
	v_mul_f32_e32 v241, v41, v231
	v_pk_mul_f32 v[240:241], v[240:241], v[36:37]
	v_cvt_pk_bf16_f32 v45, v240, v241
	v_add_u32_e32 v34, 0x4090, v1
	v_mad_i64_i32 v[34:35], s[8:9], v34, s5, v[114:115]
	v_lshl_add_u64 v[34:35], v[34:35], 0, v[116:117]
	global_store_dwordx4 v[34:35], v[42:45], off
	v_pk_mul_f32 v[230:231], v[30:31], s[98:99]
	v_exp_f32_e32 v230, v230
	v_exp_f32_e32 v231, v231
	v_add_f32_e32 v230, 1.0, v230
	v_add_f32_e32 v231, 1.0, v231
	v_rcp_f32_e32 v230, v230
	v_rcp_f32_e32 v231, v231
	v_mul_f32_e32 v234, v30, v230
	v_mul_f32_e32 v235, v31, v231
	v_pk_mul_f32 v[234:235], v[234:235], v[26:27]
	v_cvt_pk_bf16_f32 v26, v234, v235
	v_pk_mul_f32 v[230:231], v[32:33], s[98:99]
	v_exp_f32_e32 v230, v230
	v_exp_f32_e32 v231, v231
	v_add_f32_e32 v230, 1.0, v230
	v_add_f32_e32 v231, 1.0, v231
	v_rcp_f32_e32 v230, v230
	v_rcp_f32_e32 v231, v231
	v_mul_f32_e32 v236, v32, v230
	v_mul_f32_e32 v237, v33, v231
	v_pk_mul_f32 v[236:237], v[236:237], v[28:29]
	v_cvt_pk_bf16_f32 v27, v236, v237
	v_pk_mul_f32 v[230:231], v[22:23], s[98:99]
	v_exp_f32_e32 v230, v230
	v_exp_f32_e32 v231, v231
	v_add_f32_e32 v230, 1.0, v230
	v_add_f32_e32 v231, 1.0, v231
	v_rcp_f32_e32 v230, v230
	v_rcp_f32_e32 v231, v231
	v_mul_f32_e32 v238, v22, v230
	v_mul_f32_e32 v239, v23, v231
	v_pk_mul_f32 v[238:239], v[238:239], v[18:19]
	v_cvt_pk_bf16_f32 v28, v238, v239
	v_pk_mul_f32 v[230:231], v[24:25], s[98:99]
	v_exp_f32_e32 v230, v230
	v_exp_f32_e32 v231, v231
	v_add_f32_e32 v230, 1.0, v230
	v_add_f32_e32 v231, 1.0, v231
	v_rcp_f32_e32 v230, v230
	v_rcp_f32_e32 v231, v231
	v_mul_f32_e32 v240, v24, v230
	v_mul_f32_e32 v241, v25, v231
	v_pk_mul_f32 v[240:241], v[240:241], v[20:21]
	v_cvt_pk_bf16_f32 v29, v240, v241
	v_add_u32_e32 v18, 0x40a0, v1
	v_mad_i64_i32 v[18:19], s[8:9], v18, s5, v[114:115]
	v_lshl_add_u64 v[18:19], v[18:19], 0, v[116:117]
	global_store_dwordx4 v[18:19], v[26:29], off
	v_pk_mul_f32 v[230:231], v[14:15], s[98:99]
	v_exp_f32_e32 v230, v230
	v_exp_f32_e32 v231, v231
	v_add_f32_e32 v230, 1.0, v230
	v_add_f32_e32 v231, 1.0, v231
	v_rcp_f32_e32 v230, v230
	v_rcp_f32_e32 v231, v231
	v_mul_f32_e32 v234, v14, v230
	v_mul_f32_e32 v235, v15, v231
	v_pk_mul_f32 v[234:235], v[234:235], v[10:11]
	v_cvt_pk_bf16_f32 v10, v234, v235
	v_pk_mul_f32 v[230:231], v[16:17], s[98:99]
	v_exp_f32_e32 v230, v230
	v_exp_f32_e32 v231, v231
	v_add_f32_e32 v230, 1.0, v230
	v_add_f32_e32 v231, 1.0, v231
	v_rcp_f32_e32 v230, v230
	v_rcp_f32_e32 v231, v231
	v_mul_f32_e32 v236, v16, v230
	v_mul_f32_e32 v237, v17, v231
	v_pk_mul_f32 v[236:237], v[236:237], v[12:13]
	v_cvt_pk_bf16_f32 v11, v236, v237
	v_pk_mul_f32 v[230:231], v[6:7], s[98:99]
	v_exp_f32_e32 v230, v230
	v_exp_f32_e32 v231, v231
	v_add_f32_e32 v230, 1.0, v230
	v_add_f32_e32 v231, 1.0, v231
	v_rcp_f32_e32 v230, v230
	v_rcp_f32_e32 v231, v231
	v_mul_f32_e32 v238, v6, v230
	v_mul_f32_e32 v239, v7, v231
	v_pk_mul_f32 v[238:239], v[238:239], v[2:3]
	v_cvt_pk_bf16_f32 v12, v238, v239
	v_pk_mul_f32 v[230:231], v[8:9], s[98:99]
	v_exp_f32_e32 v230, v230
	v_exp_f32_e32 v231, v231
	v_add_f32_e32 v230, 1.0, v230
	v_add_f32_e32 v231, 1.0, v231
	v_rcp_f32_e32 v230, v230
	v_rcp_f32_e32 v231, v231
	v_mul_f32_e32 v240, v8, v230
	v_mul_f32_e32 v241, v9, v231
	v_pk_mul_f32 v[240:241], v[240:241], v[4:5]
	v_add_u32_e32 v1, 0x40b0, v1
	v_cvt_pk_bf16_f32 v13, v240, v241
	v_mad_i64_i32 v[2:3], s[8:9], v1, s5, v[114:115]
	v_lshl_add_u64 v[2:3], v[2:3], 0, v[116:117]
	global_store_dwordx4 v[2:3], v[10:13], off
	s_waitcnt vmcnt(0)
	s_barrier
	s_waitcnt vmcnt(0)
	s_waitcnt vmcnt(0) lgkmcnt(0)
	s_barrier
	s_mov_b64 s[8:9], exec
	v_readlane_b32 s10, v228, 2
	v_readlane_b32 s11, v228, 3
	s_and_b64 s[10:11], s[8:9], s[10:11]
	s_mov_b64 exec, s[10:11]
	s_cbranch_execz .LBB0_3407
	s_mov_b64 s[10:11], exec
	v_mbcnt_lo_u32_b32 v1, s10, 0
	buffer_wbl2 sc1
	s_waitcnt vmcnt(0)
	v_mbcnt_hi_u32_b32 v1, s11, v1
	v_cmp_eq_u32_e32 vcc, 0, v1
	s_and_b64 s[20:21], exec, vcc
	s_mov_b64 exec, s[20:21]
	s_cbranch_execz .LBB0_3407
	s_bcnt1_i32_b64 s5, s[10:11]
	v_mov_b32_e32 v1, 0
	v_mov_b32_e32 v2, s5
	global_atomic_add v1, v2, s[6:7]

.LBB0_3470:
	s_mov_b32 s98, 0xbfb8aa3b
	s_mov_b32 s99, 0xbfb8aa3b
	v_lshl_add_u32 v150, s52, 8, v1
	v_lshl_or_b32 v152, s53, 7, v131
	v_pk_mul_f32 v[230:231], v[126:127], s[98:99]
	v_exp_f32_e32 v230, v230
	v_exp_f32_e32 v231, v231
	v_add_f32_e32 v230, 1.0, v230
	v_add_f32_e32 v231, 1.0, v231
	v_rcp_f32_e32 v230, v230
	v_rcp_f32_e32 v231, v231
	v_mul_f32_e32 v234, v126, v230
	v_mul_f32_e32 v235, v127, v231
	v_pk_mul_f32 v[234:235], v[234:235], v[122:123]
	v_cvt_pk_bf16_f32 v122, v234, v235
	v_pk_mul_f32 v[230:231], v[128:129], s[98:99]
	v_exp_f32_e32 v230, v230
	v_exp_f32_e32 v231, v231
	v_add_f32_e32 v230, 1.0, v230
	v_add_f32_e32 v231, 1.0, v231
	v_rcp_f32_e32 v230, v230
	v_rcp_f32_e32 v231, v231
	v_mul_f32_e32 v236, v128, v230
	v_mul_f32_e32 v237, v129, v231
	v_pk_mul_f32 v[236:237], v[236:237], v[124:125]
	v_cvt_pk_bf16_f32 v123, v236, v237
	v_pk_mul_f32 v[230:231], v[118:119], s[98:99]
	v_exp_f32_e32 v230, v230
	v_exp_f32_e32 v231, v231
	v_add_f32_e32 v230, 1.0, v230
	v_add_f32_e32 v231, 1.0, v231
	v_rcp_f32_e32 v230, v230
	v_rcp_f32_e32 v231, v231
	v_mul_f32_e32 v238, v118, v230
	v_mul_f32_e32 v239, v119, v231
	v_pk_mul_f32 v[238:239], v[238:239], v[114:115]
	v_cvt_pk_bf16_f32 v124, v238, v239
	v_pk_mul_f32 v[230:231], v[120:121], s[98:99]
	v_exp_f32_e32 v230, v230
	v_exp_f32_e32 v231, v231
	v_add_f32_e32 v230, 1.0, v230
	v_add_f32_e32 v231, 1.0, v231
	v_rcp_f32_e32 v230, v230
	v_rcp_f32_e32 v231, v231
	v_mul_f32_e32 v240, v120, v230
	v_mul_f32_e32 v241, v121, v231
	v_pk_mul_f32 v[240:241], v[240:241], v[116:117]
	v_cvt_pk_bf16_f32 v125, v240, v241
	v_ashrrev_i32_e32 v153, 31, v152
	v_mov_b64_e32 v[114:115], s[18:19]
	v_mad_i64_i32 v[118:119], s[52:53], v150, s63, v[114:115]
	v_lshlrev_b64 v[116:117], 1, v[152:153]
	v_lshl_add_u64 v[118:119], v[118:119], 0, v[116:117]
	global_store_dwordx4 v[118:119], v[122:125], off
	s_nop 1
	v_pk_mul_f32 v[230:231], v[110:111], s[98:99]
	v_exp_f32_e32 v230, v230
	v_exp_f32_e32 v231, v231
	v_add_f32_e32 v230, 1.0, v230
	v_add_f32_e32 v231, 1.0, v231
	v_rcp_f32_e32 v230, v230
	v_rcp_f32_e32 v231, v231
	v_mul_f32_e32 v234, v110, v230
	v_mul_f32_e32 v235, v111, v231
	v_pk_mul_f32 v[234:235], v[234:235], v[106:107]
	v_cvt_pk_bf16_f32 v106, v234, v235
	v_pk_mul_f32 v[230:231], v[112:113], s[98:99]
	v_exp_f32_e32 v230, v230
	v_exp_f32_e32 v231, v231
	v_add_f32_e32 v230, 1.0, v230
	v_add_f32_e32 v231, 1.0, v231
	v_rcp_f32_e32 v230, v230
	v_rcp_f32_e32 v231, v231
	v_mul_f32_e32 v236, v112, v230
	v_mul_f32_e32 v237, v113, v231
	v_pk_mul_f32 v[236:237], v[236:237], v[108:109]
	v_cvt_pk_bf16_f32 v107, v236, v237
	v_pk_mul_f32 v[230:231], v[102:103], s[98:99]
	v_exp_f32_e32 v230, v230
	v_exp_f32_e32 v231, v231
	v_add_f32_e32 v230, 1.0, v230
	v_add_f32_e32 v231, 1.0, v231
	v_rcp_f32_e32 v230, v230
	v_rcp_f32_e32 v231, v231
	v_mul_f32_e32 v238, v102, v230
	v_mul_f32_e32 v239, v103, v231
	v_pk_mul_f32 v[238:239], v[238:239], v[98:99]
	v_cvt_pk_bf16_f32 v108, v238, v239
	v_pk_mul_f32 v[230:231], v[104:105], s[98:99]
	v_exp_f32_e32 v230, v230
	v_exp_f32_e32 v231, v231
	v_add_f32_e32 v230, 1.0, v230
	v_add_f32_e32 v231, 1.0, v231
	v_rcp_f32_e32 v230, v230
	v_rcp_f32_e32 v231, v231
	v_mul_f32_e32 v240, v104, v230
	v_mul_f32_e32 v241, v105, v231
	v_pk_mul_f32 v[240:241], v[240:241], v[100:101]
	v_cvt_pk_bf16_f32 v109, v240, v241
	v_or_b32_e32 v98, 16, v150
	v_mad_i64_i32 v[98:99], s[52:53], v98, s63, v[114:115]
	v_lshl_add_u64 v[98:99], v[98:99], 0, v[116:117]
	global_store_dwordx4 v[98:99], v[106:109], off
	v_pk_mul_f32 v[230:231], v[94:95], s[98:99]
	v_exp_f32_e32 v230, v230
	v_exp_f32_e32 v231, v231
	v_add_f32_e32 v230, 1.0, v230
	v_add_f32_e32 v231, 1.0, v231
	v_rcp_f32_e32 v230, v230
	v_rcp_f32_e32 v231, v231
	v_mul_f32_e32 v234, v94, v230
	v_mul_f32_e32 v235, v95, v231
	v_pk_mul_f32 v[234:235], v[234:235], v[90:91]
	v_cvt_pk_bf16_f32 v90, v234, v235
	v_pk_mul_f32 v[230:231], v[96:97], s[98:99]
	v_exp_f32_e32 v230, v230
	v_exp_f32_e32 v231, v231
	v_add_f32_e32 v230, 1.0, v230
	v_add_f32_e32 v231, 1.0, v231
	v_rcp_f32_e32 v230, v230
	v_rcp_f32_e32 v231, v231
	v_mul_f32_e32 v236, v96, v230
	v_mul_f32_e32 v237, v97, v231
	v_pk_mul_f32 v[236:237], v[236:237], v[92:93]
	v_cvt_pk_bf16_f32 v91, v236, v237
	v_pk_mul_f32 v[230:231], v[86:87], s[98:99]
	v_exp_f32_e32 v230, v230
	v_exp_f32_e32 v231, v231
	v_add_f32_e32 v230, 1.0, v230
	v_add_f32_e32 v231, 1.0, v231
	v_rcp_f32_e32 v230, v230
	v_rcp_f32_e32 v231, v231
	v_mul_f32_e32 v238, v86, v230
	v_mul_f32_e32 v239, v87, v231
	v_pk_mul_f32 v[238:239], v[238:239], v[82:83]
	v_cvt_pk_bf16_f32 v92, v238, v239
	v_pk_mul_f32 v[230:231], v[88:89], s[98:99]
	v_exp_f32_e32 v230, v230
	v_exp_f32_e32 v231, v231
	v_add_f32_e32 v230, 1.0, v230
	v_add_f32_e32 v231, 1.0, v231
	v_rcp_f32_e32 v230, v230
	v_rcp_f32_e32 v231, v231
	v_mul_f32_e32 v240, v88, v230
	v_mul_f32_e32 v241, v89, v231
	v_pk_mul_f32 v[240:241], v[240:241], v[84:85]
	v_cvt_pk_bf16_f32 v93, v240, v241
	v_or_b32_e32 v82, 32, v150
	v_mad_i64_i32 v[82:83], s[52:53], v82, s63, v[114:115]
	v_lshl_add_u64 v[82:83], v[82:83], 0, v[116:117]
	global_store_dwordx4 v[82:83], v[90:93], off
	v_pk_mul_f32 v[230:231], v[78:79], s[98:99]
	v_exp_f32_e32 v230, v230
	v_exp_f32_e32 v231, v231
	v_add_f32_e32 v230, 1.0, v230
	v_add_f32_e32 v231, 1.0, v231
	v_rcp_f32_e32 v230, v230
	v_rcp_f32_e32 v231, v231
	v_mul_f32_e32 v234, v78, v230
	v_mul_f32_e32 v235, v79, v231
	v_pk_mul_f32 v[234:235], v[234:235], v[74:75]
	v_cvt_pk_bf16_f32 v74, v234, v235
	v_pk_mul_f32 v[230:231], v[80:81], s[98:99]
	v_exp_f32_e32 v230, v230
	v_exp_f32_e32 v231, v231
	v_add_f32_e32 v230, 1.0, v230
	v_add_f32_e32 v231, 1.0, v231
	v_rcp_f32_e32 v230, v230
	v_rcp_f32_e32 v231, v231
	v_mul_f32_e32 v236, v80, v230
	v_mul_f32_e32 v237, v81, v231
	v_pk_mul_f32 v[236:237], v[236:237], v[76:77]
	v_cvt_pk_bf16_f32 v75, v236, v237
	v_pk_mul_f32 v[230:231], v[70:71], s[98:99]
	v_exp_f32_e32 v230, v230
	v_exp_f32_e32 v231, v231
	v_add_f32_e32 v230, 1.0, v230
	v_add_f32_e32 v231, 1.0, v231
	v_rcp_f32_e32 v230, v230
	v_rcp_f32_e32 v231, v231
	v_mul_f32_e32 v238, v70, v230
	v_mul_f32_e32 v239, v71, v231
	v_pk_mul_f32 v[238:239], v[238:239], v[66:67]
	v_cvt_pk_bf16_f32 v76, v238, v239
	v_pk_mul_f32 v[230:231], v[72:73], s[98:99]
	v_exp_f32_e32 v230, v230
	v_exp_f32_e32 v231, v231
	v_add_f32_e32 v230, 1.0, v230
	v_add_f32_e32 v231, 1.0, v231
	v_rcp_f32_e32 v230, v230
	v_rcp_f32_e32 v231, v231
	v_mul_f32_e32 v240, v72, v230
	v_mul_f32_e32 v241, v73, v231
	v_pk_mul_f32 v[240:241], v[240:241], v[68:69]
	v_cvt_pk_bf16_f32 v77, v240, v241
	v_or_b32_e32 v66, 48, v150
	v_mad_i64_i32 v[66:67], s[52:53], v66, s63, v[114:115]
	v_lshl_add_u64 v[66:67], v[66:67], 0, v[116:117]
	global_store_dwordx4 v[66:67], v[74:77], off
	v_pk_mul_f32 v[230:231], v[62:63], s[98:99]
	v_exp_f32_e32 v230, v230
	v_exp_f32_e32 v231, v231
	v_add_f32_e32 v230, 1.0, v230
	v_add_f32_e32 v231, 1.0, v231
	v_rcp_f32_e32 v230, v230
	v_rcp_f32_e32 v231, v231
	v_mul_f32_e32 v234, v62, v230
	v_mul_f32_e32 v235, v63, v231
	v_pk_mul_f32 v[234:235], v[234:235], v[58:59]
	v_cvt_pk_bf16_f32 v58, v234, v235
	v_pk_mul_f32 v[230:231], v[64:65], s[98:99]
	v_exp_f32_e32 v230, v230
	v_exp_f32_e32 v231, v231
	v_add_f32_e32 v230, 1.0, v230
	v_add_f32_e32 v231, 1.0, v231
	v_rcp_f32_e32 v230, v230
	v_rcp_f32_e32 v231, v231
	v_mul_f32_e32 v236, v64, v230
	v_mul_f32_e32 v237, v65, v231
	v_pk_mul_f32 v[236:237], v[236:237], v[60:61]
	v_cvt_pk_bf16_f32 v59, v236, v237
	v_pk_mul_f32 v[230:231], v[54:55], s[98:99]
	v_exp_f32_e32 v230, v230
	v_exp_f32_e32 v231, v231
	v_add_f32_e32 v230, 1.0, v230
	v_add_f32_e32 v231, 1.0, v231
	v_rcp_f32_e32 v230, v230
	v_rcp_f32_e32 v231, v231
	v_mul_f32_e32 v238, v54, v230
	v_mul_f32_e32 v239, v55, v231
	v_pk_mul_f32 v[238:239], v[238:239], v[50:51]
	v_cvt_pk_bf16_f32 v60, v238, v239
	v_pk_mul_f32 v[230:231], v[56:57], s[98:99]
	v_exp_f32_e32 v230, v230
	v_exp_f32_e32 v231, v231
	v_add_f32_e32 v230, 1.0, v230
	v_add_f32_e32 v231, 1.0, v231
	v_rcp_f32_e32 v230, v230
	v_rcp_f32_e32 v231, v231
	v_mul_f32_e32 v240, v56, v230
	v_mul_f32_e32 v241, v57, v231
	v_pk_mul_f32 v[240:241], v[240:241], v[52:53]
	v_add_u32_e32 v66, 0x80, v150
	v_cvt_pk_bf16_f32 v61, v240, v241
	v_mad_i64_i32 v[50:51], s[52:53], v66, s63, v[114:115]
	v_lshl_add_u64 v[50:51], v[50:51], 0, v[116:117]
	global_store_dwordx4 v[50:51], v[58:61], off
	v_pk_mul_f32 v[230:231], v[46:47], s[98:99]
	v_exp_f32_e32 v230, v230
	v_exp_f32_e32 v231, v231
	v_add_f32_e32 v230, 1.0, v230
	v_add_f32_e32 v231, 1.0, v231
	v_rcp_f32_e32 v230, v230
	v_rcp_f32_e32 v231, v231
	v_mul_f32_e32 v234, v46, v230
	v_mul_f32_e32 v235, v47, v231
	v_pk_mul_f32 v[234:235], v[234:235], v[42:43]
	v_cvt_pk_bf16_f32 v42, v234, v235
	v_pk_mul_f32 v[230:231], v[48:49], s[98:99]
	v_exp_f32_e32 v230, v230
	v_exp_f32_e32 v231, v231
	v_add_f32_e32 v230, 1.0, v230
	v_add_f32_e32 v231, 1.0, v231
	v_rcp_f32_e32 v230, v230
	v_rcp_f32_e32 v231, v231
	v_mul_f32_e32 v236, v48, v230
	v_mul_f32_e32 v237, v49, v231
	v_pk_mul_f32 v[236:237], v[236:237], v[44:45]
	v_cvt_pk_bf16_f32 v43, v236, v237
	v_pk_mul_f32 v[230:231], v[38:39], s[98:99]
	v_exp_f32_e32 v230, v230
	v_exp_f32_e32 v231, v231
	v_add_f32_e32 v230, 1.0, v230
	v_add_f32_e32 v231, 1.0, v231
	v_rcp_f32_e32 v230, v230
	v_rcp_f32_e32 v231, v231
	v_mul_f32_e32 v238, v38, v230
	v_mul_f32_e32 v239, v39, v231
	v_pk_mul_f32 v[238:239], v[238:239], v[34:35]
	v_cvt_pk_bf16_f32 v44, v238, v239
	v_pk_mul_f32 v[230:231], v[40:41], s[98:99]
	v_exp_f32_e32 v230, v230
	v_exp_f32_e32 v231, v231
	v_add_f32_e32 v230, 1.0, v230
	v_add_f32_e32 v231, 1.0, v231
	v_rcp_f32_e32 v230, v230
	v_rcp_f32_e32 v231, v231
	v_mul_f32_e32 v240, v40, v230
	v_mul_f32_e32 v241, v41, v231
	v_pk_mul_f32 v[240:241], v[240:241], v[36:37]
	v_cvt_pk_bf16_f32 v45, v240, v241
	v_add_u32_e32 v34, 0x90, v150
	v_mad_i64_i32 v[34:35], s[52:53], v34, s63, v[114:115]
	v_lshl_add_u64 v[34:35], v[34:35], 0, v[116:117]
	global_store_dwordx4 v[34:35], v[42:45], off
	v_pk_mul_f32 v[230:231], v[30:31], s[98:99]
	v_exp_f32_e32 v230, v230
	v_exp_f32_e32 v231, v231
	v_add_f32_e32 v230, 1.0, v230
	v_add_f32_e32 v231, 1.0, v231
	v_rcp_f32_e32 v230, v230
	v_rcp_f32_e32 v231, v231
	v_mul_f32_e32 v234, v30, v230
	v_mul_f32_e32 v235, v31, v231
	v_pk_mul_f32 v[234:235], v[234:235], v[26:27]
	v_cvt_pk_bf16_f32 v26, v234, v235
	v_pk_mul_f32 v[230:231], v[32:33], s[98:99]
	v_exp_f32_e32 v230, v230
	v_exp_f32_e32 v231, v231
	v_add_f32_e32 v230, 1.0, v230
	v_add_f32_e32 v231, 1.0, v231
	v_rcp_f32_e32 v230, v230
	v_rcp_f32_e32 v231, v231
	v_mul_f32_e32 v236, v32, v230
	v_mul_f32_e32 v237, v33, v231
	v_pk_mul_f32 v[236:237], v[236:237], v[28:29]
	v_cvt_pk_bf16_f32 v27, v236, v237
	v_pk_mul_f32 v[230:231], v[22:23], s[98:99]
	v_exp_f32_e32 v230, v230
	v_exp_f32_e32 v231, v231
	v_add_f32_e32 v230, 1.0, v230
	v_add_f32_e32 v231, 1.0, v231
	v_rcp_f32_e32 v230, v230
	v_rcp_f32_e32 v231, v231
	v_mul_f32_e32 v238, v22, v230
	v_mul_f32_e32 v239, v23, v231
	v_pk_mul_f32 v[238:239], v[238:239], v[18:19]
	v_cvt_pk_bf16_f32 v28, v238, v239
	v_pk_mul_f32 v[230:231], v[24:25], s[98:99]
	v_exp_f32_e32 v230, v230
	v_exp_f32_e32 v231, v231
	v_add_f32_e32 v230, 1.0, v230
	v_add_f32_e32 v231, 1.0, v231
	v_rcp_f32_e32 v230, v230
	v_rcp_f32_e32 v231, v231
	v_mul_f32_e32 v240, v24, v230
	v_mul_f32_e32 v241, v25, v231
	v_pk_mul_f32 v[240:241], v[240:241], v[20:21]
	v_cvt_pk_bf16_f32 v29, v240, v241
	v_add_u32_e32 v18, 0xa0, v150
	v_mad_i64_i32 v[18:19], s[52:53], v18, s63, v[114:115]
	v_lshl_add_u64 v[18:19], v[18:19], 0, v[116:117]
	global_store_dwordx4 v[18:19], v[26:29], off
	v_pk_mul_f32 v[230:231], v[14:15], s[98:99]
	v_exp_f32_e32 v230, v230
	v_exp_f32_e32 v231, v231
	v_add_f32_e32 v230, 1.0, v230
	v_add_f32_e32 v231, 1.0, v231
	v_rcp_f32_e32 v230, v230
	v_rcp_f32_e32 v231, v231
	v_mul_f32_e32 v234, v14, v230
	v_mul_f32_e32 v235, v15, v231
	v_pk_mul_f32 v[234:235], v[234:235], v[10:11]
	v_cvt_pk_bf16_f32 v10, v234, v235
	v_pk_mul_f32 v[230:231], v[16:17], s[98:99]
	v_exp_f32_e32 v230, v230
	v_exp_f32_e32 v231, v231
	v_add_f32_e32 v230, 1.0, v230
	v_add_f32_e32 v231, 1.0, v231
	v_rcp_f32_e32 v230, v230
	v_rcp_f32_e32 v231, v231
	v_mul_f32_e32 v236, v16, v230
	v_mul_f32_e32 v237, v17, v231
	v_pk_mul_f32 v[236:237], v[236:237], v[12:13]
	v_cvt_pk_bf16_f32 v11, v236, v237
	v_pk_mul_f32 v[230:231], v[6:7], s[98:99]
	v_exp_f32_e32 v230, v230
	v_exp_f32_e32 v231, v231
	v_add_f32_e32 v230, 1.0, v230
	v_add_f32_e32 v231, 1.0, v231
	v_rcp_f32_e32 v230, v230
	v_rcp_f32_e32 v231, v231
	v_mul_f32_e32 v238, v6, v230
	v_mul_f32_e32 v239, v7, v231
	v_pk_mul_f32 v[238:239], v[238:239], v[2:3]
	v_cvt_pk_bf16_f32 v12, v238, v239
	v_pk_mul_f32 v[230:231], v[8:9], s[98:99]
	v_exp_f32_e32 v230, v230
	v_exp_f32_e32 v231, v231
	v_add_f32_e32 v230, 1.0, v230
	v_add_f32_e32 v231, 1.0, v231
	v_rcp_f32_e32 v230, v230
	v_rcp_f32_e32 v231, v231
	v_mul_f32_e32 v240, v8, v230
	v_mul_f32_e32 v241, v9, v231
	v_pk_mul_f32 v[240:241], v[240:241], v[4:5]
	v_cvt_pk_bf16_f32 v13, v240, v241
	v_add_u32_e32 v2, 0xb0, v150
	v_mad_i64_i32 v[2:3], s[52:53], v2, s63, v[114:115]
	v_lshl_add_u64 v[2:3], v[2:3], 0, v[116:117]
	s_mov_b64 s[52:53], -1
	s_and_b64 vcc, exec, s[48:49]
	global_store_dwordx4 v[2:3], v[10:13], off
	s_cbranch_vccz .LBB0_3459
	s_andn2_b64 vcc, exec, s[6:7]
	s_cbranch_vccnz .LBB0_3458
	s_barrier
	s_branch .LBB0_3458

.LBB0_5756:
	s_mov_b32 s98, 0xbfb8aa3b
	s_mov_b32 s99, 0xbfb8aa3b
	s_lshl_b32 s5, s82, 7
	s_or_b32 s5, s35, s5
	v_or_b32_e32 v130, s5, v142
	v_add_u32_e32 v132, 0x4000, v1
	v_pk_mul_f32 v[230:231], v[126:127], s[98:99]
	v_exp_f32_e32 v230, v230
	v_exp_f32_e32 v231, v231
	v_add_f32_e32 v230, 1.0, v230
	v_add_f32_e32 v231, 1.0, v231
	v_rcp_f32_e32 v230, v230
	v_rcp_f32_e32 v231, v231
	v_mul_f32_e32 v234, v126, v230
	v_mul_f32_e32 v235, v127, v231
	v_pk_mul_f32 v[234:235], v[234:235], v[122:123]
	v_cvt_pk_bf16_f32 v122, v234, v235
	v_pk_mul_f32 v[230:231], v[128:129], s[98:99]
	v_exp_f32_e32 v230, v230
	v_exp_f32_e32 v231, v231
	v_add_f32_e32 v230, 1.0, v230
	v_add_f32_e32 v231, 1.0, v231
	v_rcp_f32_e32 v230, v230
	v_rcp_f32_e32 v231, v231
	v_mul_f32_e32 v236, v128, v230
	v_mul_f32_e32 v237, v129, v231
	v_pk_mul_f32 v[236:237], v[236:237], v[124:125]
	v_cvt_pk_bf16_f32 v123, v236, v237
	v_pk_mul_f32 v[230:231], v[118:119], s[98:99]
	v_exp_f32_e32 v230, v230
	v_exp_f32_e32 v231, v231
	v_add_f32_e32 v230, 1.0, v230
	v_add_f32_e32 v231, 1.0, v231
	v_rcp_f32_e32 v230, v230
	v_rcp_f32_e32 v231, v231
	v_mul_f32_e32 v238, v118, v230
	v_mul_f32_e32 v239, v119, v231
	v_pk_mul_f32 v[238:239], v[238:239], v[114:115]
	v_cvt_pk_bf16_f32 v124, v238, v239
	v_pk_mul_f32 v[230:231], v[120:121], s[98:99]
	v_exp_f32_e32 v230, v230
	v_exp_f32_e32 v231, v231
	v_add_f32_e32 v230, 1.0, v230
	v_add_f32_e32 v231, 1.0, v231
	v_rcp_f32_e32 v230, v230
	v_rcp_f32_e32 v231, v231
	v_mul_f32_e32 v240, v120, v230
	v_mul_f32_e32 v241, v121, v231
	v_pk_mul_f32 v[240:241], v[240:241], v[116:117]
	v_cvt_pk_bf16_f32 v125, v240, v241
	v_ashrrev_i32_e32 v131, 31, v130
	s_movk_i32 s5, 0x1600
	v_mov_b64_e32 v[114:115], s[18:19]
	v_mad_i64_i32 v[118:119], s[8:9], v132, s5, v[114:115]
	v_lshlrev_b64 v[116:117], 1, v[130:131]
	v_lshl_add_u64 v[118:119], v[118:119], 0, v[116:117]
	global_store_dwordx4 v[118:119], v[122:125], off
	s_nop 1
	v_pk_mul_f32 v[230:231], v[110:111], s[98:99]
	v_exp_f32_e32 v230, v230
	v_exp_f32_e32 v231, v231
	v_add_f32_e32 v230, 1.0, v230
	v_add_f32_e32 v231, 1.0, v231
	v_rcp_f32_e32 v230, v230
	v_rcp_f32_e32 v231, v231
	v_mul_f32_e32 v234, v110, v230
	v_mul_f32_e32 v235, v111, v231
	v_pk_mul_f32 v[234:235], v[234:235], v[106:107]
	v_cvt_pk_bf16_f32 v106, v234, v235
	v_pk_mul_f32 v[230:231], v[112:113], s[98:99]
	v_exp_f32_e32 v230, v230
	v_exp_f32_e32 v231, v231
	v_add_f32_e32 v230, 1.0, v230
	v_add_f32_e32 v231, 1.0, v231
	v_rcp_f32_e32 v230, v230
	v_rcp_f32_e32 v231, v231
	v_mul_f32_e32 v236, v112, v230
	v_mul_f32_e32 v237, v113, v231
	v_pk_mul_f32 v[236:237], v[236:237], v[108:109]
	v_cvt_pk_bf16_f32 v107, v236, v237
	v_pk_mul_f32 v[230:231], v[102:103], s[98:99]
	v_exp_f32_e32 v230, v230
	v_exp_f32_e32 v231, v231
	v_add_f32_e32 v230, 1.0, v230
	v_add_f32_e32 v231, 1.0, v231
	v_rcp_f32_e32 v230, v230
	v_rcp_f32_e32 v231, v231
	v_mul_f32_e32 v238, v102, v230
	v_mul_f32_e32 v239, v103, v231
	v_pk_mul_f32 v[238:239], v[238:239], v[98:99]
	v_cvt_pk_bf16_f32 v108, v238, v239
	v_pk_mul_f32 v[230:231], v[104:105], s[98:99]
	v_exp_f32_e32 v230, v230
	v_exp_f32_e32 v231, v231
	v_add_f32_e32 v230, 1.0, v230
	v_add_f32_e32 v231, 1.0, v231
	v_rcp_f32_e32 v230, v230
	v_rcp_f32_e32 v231, v231
	v_mul_f32_e32 v240, v104, v230
	v_mul_f32_e32 v241, v105, v231
	v_pk_mul_f32 v[240:241], v[240:241], v[100:101]
	v_cvt_pk_bf16_f32 v109, v240, v241
	v_add_u32_e32 v98, 0x4010, v1
	v_mad_i64_i32 v[98:99], s[8:9], v98, s5, v[114:115]
	v_lshl_add_u64 v[98:99], v[98:99], 0, v[116:117]
	global_store_dwordx4 v[98:99], v[106:109], off
	v_pk_mul_f32 v[230:231], v[94:95], s[98:99]
	v_exp_f32_e32 v230, v230
	v_exp_f32_e32 v231, v231
	v_add_f32_e32 v230, 1.0, v230
	v_add_f32_e32 v231, 1.0, v231
	v_rcp_f32_e32 v230, v230
	v_rcp_f32_e32 v231, v231
	v_mul_f32_e32 v234, v94, v230
	v_mul_f32_e32 v235, v95, v231
	v_pk_mul_f32 v[234:235], v[234:235], v[90:91]
	v_cvt_pk_bf16_f32 v90, v234, v235
	v_pk_mul_f32 v[230:231], v[96:97], s[98:99]
	v_exp_f32_e32 v230, v230
	v_exp_f32_e32 v231, v231
	v_add_f32_e32 v230, 1.0, v230
	v_add_f32_e32 v231, 1.0, v231
	v_rcp_f32_e32 v230, v230
	v_rcp_f32_e32 v231, v231
	v_mul_f32_e32 v236, v96, v230
	v_mul_f32_e32 v237, v97, v231
	v_pk_mul_f32 v[236:237], v[236:237], v[92:93]
	v_cvt_pk_bf16_f32 v91, v236, v237
	v_pk_mul_f32 v[230:231], v[86:87], s[98:99]
	v_exp_f32_e32 v230, v230
	v_exp_f32_e32 v231, v231
	v_add_f32_e32 v230, 1.0, v230
	v_add_f32_e32 v231, 1.0, v231
	v_rcp_f32_e32 v230, v230
	v_rcp_f32_e32 v231, v231
	v_mul_f32_e32 v238, v86, v230
	v_mul_f32_e32 v239, v87, v231
	v_pk_mul_f32 v[238:239], v[238:239], v[82:83]
	v_cvt_pk_bf16_f32 v92, v238, v239
	v_pk_mul_f32 v[230:231], v[88:89], s[98:99]
	v_exp_f32_e32 v230, v230
	v_exp_f32_e32 v231, v231
	v_add_f32_e32 v230, 1.0, v230
	v_add_f32_e32 v231, 1.0, v231
	v_rcp_f32_e32 v230, v230
	v_rcp_f32_e32 v231, v231
	v_mul_f32_e32 v240, v88, v230
	v_mul_f32_e32 v241, v89, v231
	v_pk_mul_f32 v[240:241], v[240:241], v[84:85]
	v_cvt_pk_bf16_f32 v93, v240, v241
	v_add_u32_e32 v82, 0x4020, v1
	v_mad_i64_i32 v[82:83], s[8:9], v82, s5, v[114:115]
	v_lshl_add_u64 v[82:83], v[82:83], 0, v[116:117]
	global_store_dwordx4 v[82:83], v[90:93], off
	v_pk_mul_f32 v[230:231], v[78:79], s[98:99]
	v_exp_f32_e32 v230, v230
	v_exp_f32_e32 v231, v231
	v_add_f32_e32 v230, 1.0, v230
	v_add_f32_e32 v231, 1.0, v231
	v_rcp_f32_e32 v230, v230
	v_rcp_f32_e32 v231, v231
	v_mul_f32_e32 v234, v78, v230
	v_mul_f32_e32 v235, v79, v231
	v_pk_mul_f32 v[234:235], v[234:235], v[74:75]
	v_cvt_pk_bf16_f32 v74, v234, v235
	v_pk_mul_f32 v[230:231], v[80:81], s[98:99]
	v_exp_f32_e32 v230, v230
	v_exp_f32_e32 v231, v231
	v_add_f32_e32 v230, 1.0, v230
	v_add_f32_e32 v231, 1.0, v231
	v_rcp_f32_e32 v230, v230
	v_rcp_f32_e32 v231, v231
	v_mul_f32_e32 v236, v80, v230
	v_mul_f32_e32 v237, v81, v231
	v_pk_mul_f32 v[236:237], v[236:237], v[76:77]
	v_cvt_pk_bf16_f32 v75, v236, v237
	v_pk_mul_f32 v[230:231], v[70:71], s[98:99]
	v_exp_f32_e32 v230, v230
	v_exp_f32_e32 v231, v231
	v_add_f32_e32 v230, 1.0, v230
	v_add_f32_e32 v231, 1.0, v231
	v_rcp_f32_e32 v230, v230
	v_rcp_f32_e32 v231, v231
	v_mul_f32_e32 v238, v70, v230
	v_mul_f32_e32 v239, v71, v231
	v_pk_mul_f32 v[238:239], v[238:239], v[66:67]
	v_cvt_pk_bf16_f32 v76, v238, v239
	v_pk_mul_f32 v[230:231], v[72:73], s[98:99]
	v_exp_f32_e32 v230, v230
	v_exp_f32_e32 v231, v231
	v_add_f32_e32 v230, 1.0, v230
	v_add_f32_e32 v231, 1.0, v231
	v_rcp_f32_e32 v230, v230
	v_rcp_f32_e32 v231, v231
	v_mul_f32_e32 v240, v72, v230
	v_mul_f32_e32 v241, v73, v231
	v_pk_mul_f32 v[240:241], v[240:241], v[68:69]
	v_cvt_pk_bf16_f32 v77, v240, v241
	v_add_u32_e32 v66, 0x4030, v1
	v_mad_i64_i32 v[66:67], s[8:9], v66, s5, v[114:115]
	v_lshl_add_u64 v[66:67], v[66:67], 0, v[116:117]
	global_store_dwordx4 v[66:67], v[74:77], off
	v_pk_mul_f32 v[230:231], v[62:63], s[98:99]
	v_exp_f32_e32 v230, v230
	v_exp_f32_e32 v231, v231
	v_add_f32_e32 v230, 1.0, v230
	v_add_f32_e32 v231, 1.0, v231
	v_rcp_f32_e32 v230, v230
	v_rcp_f32_e32 v231, v231
	v_mul_f32_e32 v234, v62, v230
	v_mul_f32_e32 v235, v63, v231
	v_pk_mul_f32 v[234:235], v[234:235], v[58:59]
	v_cvt_pk_bf16_f32 v58, v234, v235
	v_pk_mul_f32 v[230:231], v[64:65], s[98:99]
	v_exp_f32_e32 v230, v230
	v_exp_f32_e32 v231, v231
	v_add_f32_e32 v230, 1.0, v230
	v_add_f32_e32 v231, 1.0, v231
	v_rcp_f32_e32 v230, v230
	v_rcp_f32_e32 v231, v231
	v_mul_f32_e32 v236, v64, v230
	v_mul_f32_e32 v237, v65, v231
	v_pk_mul_f32 v[236:237], v[236:237], v[60:61]
	v_cvt_pk_bf16_f32 v59, v236, v237
	v_pk_mul_f32 v[230:231], v[54:55], s[98:99]
	v_exp_f32_e32 v230, v230
	v_exp_f32_e32 v231, v231
	v_add_f32_e32 v230, 1.0, v230
	v_add_f32_e32 v231, 1.0, v231
	v_rcp_f32_e32 v230, v230
	v_rcp_f32_e32 v231, v231
	v_mul_f32_e32 v238, v54, v230
	v_mul_f32_e32 v239, v55, v231
	v_pk_mul_f32 v[238:239], v[238:239], v[50:51]
	v_cvt_pk_bf16_f32 v60, v238, v239
	v_pk_mul_f32 v[230:231], v[56:57], s[98:99]
	v_exp_f32_e32 v230, v230
	v_exp_f32_e32 v231, v231
	v_add_f32_e32 v230, 1.0, v230
	v_add_f32_e32 v231, 1.0, v231
	v_rcp_f32_e32 v230, v230
	v_rcp_f32_e32 v231, v231
	v_mul_f32_e32 v240, v56, v230
	v_mul_f32_e32 v241, v57, v231
	v_pk_mul_f32 v[240:241], v[240:241], v[52:53]
	v_add_u32_e32 v66, 0x4080, v1
	v_cvt_pk_bf16_f32 v61, v240, v241
	v_mad_i64_i32 v[50:51], s[8:9], v66, s5, v[114:115]
	v_lshl_add_u64 v[50:51], v[50:51], 0, v[116:117]
	global_store_dwordx4 v[50:51], v[58:61], off
	v_pk_mul_f32 v[230:231], v[46:47], s[98:99]
	v_exp_f32_e32 v230, v230
	v_exp_f32_e32 v231, v231
	v_add_f32_e32 v230, 1.0, v230
	v_add_f32_e32 v231, 1.0, v231
	v_rcp_f32_e32 v230, v230
	v_rcp_f32_e32 v231, v231
	v_mul_f32_e32 v234, v46, v230
	v_mul_f32_e32 v235, v47, v231
	v_pk_mul_f32 v[234:235], v[234:235], v[42:43]
	v_cvt_pk_bf16_f32 v42, v234, v235
	v_pk_mul_f32 v[230:231], v[48:49], s[98:99]
	v_exp_f32_e32 v230, v230
	v_exp_f32_e32 v231, v231
	v_add_f32_e32 v230, 1.0, v230
	v_add_f32_e32 v231, 1.0, v231
	v_rcp_f32_e32 v230, v230
	v_rcp_f32_e32 v231, v231
	v_mul_f32_e32 v236, v48, v230
	v_mul_f32_e32 v237, v49, v231
	v_pk_mul_f32 v[236:237], v[236:237], v[44:45]
	v_cvt_pk_bf16_f32 v43, v236, v237
	v_pk_mul_f32 v[230:231], v[38:39], s[98:99]
	v_exp_f32_e32 v230, v230
	v_exp_f32_e32 v231, v231
	v_add_f32_e32 v230, 1.0, v230
	v_add_f32_e32 v231, 1.0, v231
	v_rcp_f32_e32 v230, v230
	v_rcp_f32_e32 v231, v231
	v_mul_f32_e32 v238, v38, v230
	v_mul_f32_e32 v239, v39, v231
	v_pk_mul_f32 v[238:239], v[238:239], v[34:35]
	v_cvt_pk_bf16_f32 v44, v238, v239
	v_pk_mul_f32 v[230:231], v[40:41], s[98:99]
	v_exp_f32_e32 v230, v230
	v_exp_f32_e32 v231, v231
	v_add_f32_e32 v230, 1.0, v230
	v_add_f32_e32 v231, 1.0, v231
	v_rcp_f32_e32 v230, v230
	v_rcp_f32_e32 v231, v231
	v_mul_f32_e32 v240, v40, v230
	v_mul_f32_e32 v241, v41, v231
	v_pk_mul_f32 v[240:241], v[240:241], v[36:37]
	v_cvt_pk_bf16_f32 v45, v240, v241
	v_add_u32_e32 v34, 0x4090, v1
	v_mad_i64_i32 v[34:35], s[8:9], v34, s5, v[114:115]
	v_lshl_add_u64 v[34:35], v[34:35], 0, v[116:117]
	global_store_dwordx4 v[34:35], v[42:45], off
	v_pk_mul_f32 v[230:231], v[30:31], s[98:99]
	v_exp_f32_e32 v230, v230
	v_exp_f32_e32 v231, v231
	v_add_f32_e32 v230, 1.0, v230
	v_add_f32_e32 v231, 1.0, v231
	v_rcp_f32_e32 v230, v230
	v_rcp_f32_e32 v231, v231
	v_mul_f32_e32 v234, v30, v230
	v_mul_f32_e32 v235, v31, v231
	v_pk_mul_f32 v[234:235], v[234:235], v[26:27]
	v_cvt_pk_bf16_f32 v26, v234, v235
	v_pk_mul_f32 v[230:231], v[32:33], s[98:99]
	v_exp_f32_e32 v230, v230
	v_exp_f32_e32 v231, v231
	v_add_f32_e32 v230, 1.0, v230
	v_add_f32_e32 v231, 1.0, v231
	v_rcp_f32_e32 v230, v230
	v_rcp_f32_e32 v231, v231
	v_mul_f32_e32 v236, v32, v230
	v_mul_f32_e32 v237, v33, v231
	v_pk_mul_f32 v[236:237], v[236:237], v[28:29]
	v_cvt_pk_bf16_f32 v27, v236, v237
	v_pk_mul_f32 v[230:231], v[22:23], s[98:99]
	v_exp_f32_e32 v230, v230
	v_exp_f32_e32 v231, v231
	v_add_f32_e32 v230, 1.0, v230
	v_add_f32_e32 v231, 1.0, v231
	v_rcp_f32_e32 v230, v230
	v_rcp_f32_e32 v231, v231
	v_mul_f32_e32 v238, v22, v230
	v_mul_f32_e32 v239, v23, v231
	v_pk_mul_f32 v[238:239], v[238:239], v[18:19]
	v_cvt_pk_bf16_f32 v28, v238, v239
	v_pk_mul_f32 v[230:231], v[24:25], s[98:99]
	v_exp_f32_e32 v230, v230
	v_exp_f32_e32 v231, v231
	v_add_f32_e32 v230, 1.0, v230
	v_add_f32_e32 v231, 1.0, v231
	v_rcp_f32_e32 v230, v230
	v_rcp_f32_e32 v231, v231
	v_mul_f32_e32 v240, v24, v230
	v_mul_f32_e32 v241, v25, v231
	v_pk_mul_f32 v[240:241], v[240:241], v[20:21]
	v_cvt_pk_bf16_f32 v29, v240, v241
	v_add_u32_e32 v18, 0x40a0, v1
	v_mad_i64_i32 v[18:19], s[8:9], v18, s5, v[114:115]
	v_lshl_add_u64 v[18:19], v[18:19], 0, v[116:117]
	global_store_dwordx4 v[18:19], v[26:29], off
	v_pk_mul_f32 v[230:231], v[14:15], s[98:99]
	v_exp_f32_e32 v230, v230
	v_exp_f32_e32 v231, v231
	v_add_f32_e32 v230, 1.0, v230
	v_add_f32_e32 v231, 1.0, v231
	v_rcp_f32_e32 v230, v230
	v_rcp_f32_e32 v231, v231
	v_mul_f32_e32 v234, v14, v230
	v_mul_f32_e32 v235, v15, v231
	v_pk_mul_f32 v[234:235], v[234:235], v[10:11]
	v_cvt_pk_bf16_f32 v10, v234, v235
	v_pk_mul_f32 v[230:231], v[16:17], s[98:99]
	v_exp_f32_e32 v230, v230
	v_exp_f32_e32 v231, v231
	v_add_f32_e32 v230, 1.0, v230
	v_add_f32_e32 v231, 1.0, v231
	v_rcp_f32_e32 v230, v230
	v_rcp_f32_e32 v231, v231
	v_mul_f32_e32 v236, v16, v230
	v_mul_f32_e32 v237, v17, v231
	v_pk_mul_f32 v[236:237], v[236:237], v[12:13]
	v_cvt_pk_bf16_f32 v11, v236, v237
	v_pk_mul_f32 v[230:231], v[6:7], s[98:99]
	v_exp_f32_e32 v230, v230
	v_exp_f32_e32 v231, v231
	v_add_f32_e32 v230, 1.0, v230
	v_add_f32_e32 v231, 1.0, v231
	v_rcp_f32_e32 v230, v230
	v_rcp_f32_e32 v231, v231
	v_mul_f32_e32 v238, v6, v230
	v_mul_f32_e32 v239, v7, v231
	v_pk_mul_f32 v[238:239], v[238:239], v[2:3]
	v_cvt_pk_bf16_f32 v12, v238, v239
	v_pk_mul_f32 v[230:231], v[8:9], s[98:99]
	v_exp_f32_e32 v230, v230
	v_exp_f32_e32 v231, v231
	v_add_f32_e32 v230, 1.0, v230
	v_add_f32_e32 v231, 1.0, v231
	v_rcp_f32_e32 v230, v230
	v_rcp_f32_e32 v231, v231
	v_mul_f32_e32 v240, v8, v230
	v_mul_f32_e32 v241, v9, v231
	v_pk_mul_f32 v[240:241], v[240:241], v[4:5]
	v_add_u32_e32 v1, 0x40b0, v1
	v_cvt_pk_bf16_f32 v13, v240, v241
	v_mad_i64_i32 v[2:3], s[8:9], v1, s5, v[114:115]
	v_lshl_add_u64 v[2:3], v[2:3], 0, v[116:117]
	global_store_dwordx4 v[2:3], v[10:13], off
	s_waitcnt vmcnt(0)
	s_barrier
	s_waitcnt vmcnt(0)
	s_waitcnt vmcnt(0) lgkmcnt(0)
	s_barrier
	s_mov_b64 s[8:9], exec
	v_readlane_b32 s10, v228, 2
	v_readlane_b32 s11, v228, 3
	s_and_b64 s[10:11], s[8:9], s[10:11]
	s_mov_b64 exec, s[10:11]
	s_cbranch_execz .LBB0_5759
	s_mov_b64 s[10:11], exec
	v_mbcnt_lo_u32_b32 v1, s10, 0
	buffer_wbl2 sc1
	s_waitcnt vmcnt(0)
	v_mbcnt_hi_u32_b32 v1, s11, v1
	v_cmp_eq_u32_e32 vcc, 0, v1
	s_and_b64 s[12:13], exec, vcc
	s_mov_b64 exec, s[12:13]
	s_cbranch_execz .LBB0_5759
	s_bcnt1_i32_b64 s5, s[10:11]
	v_mov_b32_e32 v1, 0
	v_mov_b32_e32 v2, s5
	global_atomic_add v1, v2, s[6:7]

.LBB0_5822:
	s_mov_b32 s98, 0xbfb8aa3b
	s_mov_b32 s99, 0xbfb8aa3b
	v_lshl_add_u32 v148, s42, 8, v1
	v_lshl_or_b32 v150, s43, 7, v142
	v_pk_mul_f32 v[230:231], v[126:127], s[98:99]
	v_exp_f32_e32 v230, v230
	v_exp_f32_e32 v231, v231
	v_add_f32_e32 v230, 1.0, v230
	v_add_f32_e32 v231, 1.0, v231
	v_rcp_f32_e32 v230, v230
	v_rcp_f32_e32 v231, v231
	v_mul_f32_e32 v234, v126, v230
	v_mul_f32_e32 v235, v127, v231
	v_pk_mul_f32 v[234:235], v[234:235], v[122:123]
	v_cvt_pk_bf16_f32 v122, v234, v235
	v_pk_mul_f32 v[230:231], v[128:129], s[98:99]
	v_exp_f32_e32 v230, v230
	v_exp_f32_e32 v231, v231
	v_add_f32_e32 v230, 1.0, v230
	v_add_f32_e32 v231, 1.0, v231
	v_rcp_f32_e32 v230, v230
	v_rcp_f32_e32 v231, v231
	v_mul_f32_e32 v236, v128, v230
	v_mul_f32_e32 v237, v129, v231
	v_pk_mul_f32 v[236:237], v[236:237], v[124:125]
	v_cvt_pk_bf16_f32 v123, v236, v237
	v_pk_mul_f32 v[230:231], v[118:119], s[98:99]
	v_exp_f32_e32 v230, v230
	v_exp_f32_e32 v231, v231
	v_add_f32_e32 v230, 1.0, v230
	v_add_f32_e32 v231, 1.0, v231
	v_rcp_f32_e32 v230, v230
	v_rcp_f32_e32 v231, v231
	v_mul_f32_e32 v238, v118, v230
	v_mul_f32_e32 v239, v119, v231
	v_pk_mul_f32 v[238:239], v[238:239], v[114:115]
	v_cvt_pk_bf16_f32 v124, v238, v239
	v_pk_mul_f32 v[230:231], v[120:121], s[98:99]
	v_exp_f32_e32 v230, v230
	v_exp_f32_e32 v231, v231
	v_add_f32_e32 v230, 1.0, v230
	v_add_f32_e32 v231, 1.0, v231
	v_rcp_f32_e32 v230, v230
	v_rcp_f32_e32 v231, v231
	v_mul_f32_e32 v240, v120, v230
	v_mul_f32_e32 v241, v121, v231
	v_pk_mul_f32 v[240:241], v[240:241], v[116:117]
	v_cvt_pk_bf16_f32 v125, v240, v241
	v_ashrrev_i32_e32 v151, 31, v150
	v_mov_b64_e32 v[114:115], s[18:19]
	v_mad_i64_i32 v[118:119], s[42:43], v148, s59, v[114:115]
	v_lshlrev_b64 v[116:117], 1, v[150:151]
	v_lshl_add_u64 v[118:119], v[118:119], 0, v[116:117]
	global_store_dwordx4 v[118:119], v[122:125], off
	s_nop 1
	v_pk_mul_f32 v[230:231], v[110:111], s[98:99]
	v_exp_f32_e32 v230, v230
	v_exp_f32_e32 v231, v231
	v_add_f32_e32 v230, 1.0, v230
	v_add_f32_e32 v231, 1.0, v231
	v_rcp_f32_e32 v230, v230
	v_rcp_f32_e32 v231, v231
	v_mul_f32_e32 v234, v110, v230
	v_mul_f32_e32 v235, v111, v231
	v_pk_mul_f32 v[234:235], v[234:235], v[106:107]
	v_cvt_pk_bf16_f32 v106, v234, v235
	v_pk_mul_f32 v[230:231], v[112:113], s[98:99]
	v_exp_f32_e32 v230, v230
	v_exp_f32_e32 v231, v231
	v_add_f32_e32 v230, 1.0, v230
	v_add_f32_e32 v231, 1.0, v231
	v_rcp_f32_e32 v230, v230
	v_rcp_f32_e32 v231, v231
	v_mul_f32_e32 v236, v112, v230
	v_mul_f32_e32 v237, v113, v231
	v_pk_mul_f32 v[236:237], v[236:237], v[108:109]
	v_cvt_pk_bf16_f32 v107, v236, v237
	v_pk_mul_f32 v[230:231], v[102:103], s[98:99]
	v_exp_f32_e32 v230, v230
	v_exp_f32_e32 v231, v231
	v_add_f32_e32 v230, 1.0, v230
	v_add_f32_e32 v231, 1.0, v231
	v_rcp_f32_e32 v230, v230
	v_rcp_f32_e32 v231, v231
	v_mul_f32_e32 v238, v102, v230
	v_mul_f32_e32 v239, v103, v231
	v_pk_mul_f32 v[238:239], v[238:239], v[98:99]
	v_cvt_pk_bf16_f32 v108, v238, v239
	v_pk_mul_f32 v[230:231], v[104:105], s[98:99]
	v_exp_f32_e32 v230, v230
	v_exp_f32_e32 v231, v231
	v_add_f32_e32 v230, 1.0, v230
	v_add_f32_e32 v231, 1.0, v231
	v_rcp_f32_e32 v230, v230
	v_rcp_f32_e32 v231, v231
	v_mul_f32_e32 v240, v104, v230
	v_mul_f32_e32 v241, v105, v231
	v_pk_mul_f32 v[240:241], v[240:241], v[100:101]
	v_cvt_pk_bf16_f32 v109, v240, v241
	v_or_b32_e32 v98, 16, v148
	v_mad_i64_i32 v[98:99], s[42:43], v98, s59, v[114:115]
	v_lshl_add_u64 v[98:99], v[98:99], 0, v[116:117]
	global_store_dwordx4 v[98:99], v[106:109], off
	v_pk_mul_f32 v[230:231], v[94:95], s[98:99]
	v_exp_f32_e32 v230, v230
	v_exp_f32_e32 v231, v231
	v_add_f32_e32 v230, 1.0, v230
	v_add_f32_e32 v231, 1.0, v231
	v_rcp_f32_e32 v230, v230
	v_rcp_f32_e32 v231, v231
	v_mul_f32_e32 v234, v94, v230
	v_mul_f32_e32 v235, v95, v231
	v_pk_mul_f32 v[234:235], v[234:235], v[90:91]
	v_cvt_pk_bf16_f32 v90, v234, v235
	v_pk_mul_f32 v[230:231], v[96:97], s[98:99]
	v_exp_f32_e32 v230, v230
	v_exp_f32_e32 v231, v231
	v_add_f32_e32 v230, 1.0, v230
	v_add_f32_e32 v231, 1.0, v231
	v_rcp_f32_e32 v230, v230
	v_rcp_f32_e32 v231, v231
	v_mul_f32_e32 v236, v96, v230
	v_mul_f32_e32 v237, v97, v231
	v_pk_mul_f32 v[236:237], v[236:237], v[92:93]
	v_cvt_pk_bf16_f32 v91, v236, v237
	v_pk_mul_f32 v[230:231], v[86:87], s[98:99]
	v_exp_f32_e32 v230, v230
	v_exp_f32_e32 v231, v231
	v_add_f32_e32 v230, 1.0, v230
	v_add_f32_e32 v231, 1.0, v231
	v_rcp_f32_e32 v230, v230
	v_rcp_f32_e32 v231, v231
	v_mul_f32_e32 v238, v86, v230
	v_mul_f32_e32 v239, v87, v231
	v_pk_mul_f32 v[238:239], v[238:239], v[82:83]
	v_cvt_pk_bf16_f32 v92, v238, v239
	v_pk_mul_f32 v[230:231], v[88:89], s[98:99]
	v_exp_f32_e32 v230, v230
	v_exp_f32_e32 v231, v231
	v_add_f32_e32 v230, 1.0, v230
	v_add_f32_e32 v231, 1.0, v231
	v_rcp_f32_e32 v230, v230
	v_rcp_f32_e32 v231, v231
	v_mul_f32_e32 v240, v88, v230
	v_mul_f32_e32 v241, v89, v231
	v_pk_mul_f32 v[240:241], v[240:241], v[84:85]
	v_cvt_pk_bf16_f32 v93, v240, v241
	v_or_b32_e32 v82, 32, v148
	v_mad_i64_i32 v[82:83], s[42:43], v82, s59, v[114:115]
	v_lshl_add_u64 v[82:83], v[82:83], 0, v[116:117]
	global_store_dwordx4 v[82:83], v[90:93], off
	v_pk_mul_f32 v[230:231], v[78:79], s[98:99]
	v_exp_f32_e32 v230, v230
	v_exp_f32_e32 v231, v231
	v_add_f32_e32 v230, 1.0, v230
	v_add_f32_e32 v231, 1.0, v231
	v_rcp_f32_e32 v230, v230
	v_rcp_f32_e32 v231, v231
	v_mul_f32_e32 v234, v78, v230
	v_mul_f32_e32 v235, v79, v231
	v_pk_mul_f32 v[234:235], v[234:235], v[74:75]
	v_cvt_pk_bf16_f32 v74, v234, v235
	v_pk_mul_f32 v[230:231], v[80:81], s[98:99]
	v_exp_f32_e32 v230, v230
	v_exp_f32_e32 v231, v231
	v_add_f32_e32 v230, 1.0, v230
	v_add_f32_e32 v231, 1.0, v231
	v_rcp_f32_e32 v230, v230
	v_rcp_f32_e32 v231, v231
	v_mul_f32_e32 v236, v80, v230
	v_mul_f32_e32 v237, v81, v231
	v_pk_mul_f32 v[236:237], v[236:237], v[76:77]
	v_cvt_pk_bf16_f32 v75, v236, v237
	v_pk_mul_f32 v[230:231], v[70:71], s[98:99]
	v_exp_f32_e32 v230, v230
	v_exp_f32_e32 v231, v231
	v_add_f32_e32 v230, 1.0, v230
	v_add_f32_e32 v231, 1.0, v231
	v_rcp_f32_e32 v230, v230
	v_rcp_f32_e32 v231, v231
	v_mul_f32_e32 v238, v70, v230
	v_mul_f32_e32 v239, v71, v231
	v_pk_mul_f32 v[238:239], v[238:239], v[66:67]
	v_cvt_pk_bf16_f32 v76, v238, v239
	v_pk_mul_f32 v[230:231], v[72:73], s[98:99]
	v_exp_f32_e32 v230, v230
	v_exp_f32_e32 v231, v231
	v_add_f32_e32 v230, 1.0, v230
	v_add_f32_e32 v231, 1.0, v231
	v_rcp_f32_e32 v230, v230
	v_rcp_f32_e32 v231, v231
	v_mul_f32_e32 v240, v72, v230
	v_mul_f32_e32 v241, v73, v231
	v_pk_mul_f32 v[240:241], v[240:241], v[68:69]
	v_cvt_pk_bf16_f32 v77, v240, v241
	v_or_b32_e32 v66, 48, v148
	v_mad_i64_i32 v[66:67], s[42:43], v66, s59, v[114:115]
	v_lshl_add_u64 v[66:67], v[66:67], 0, v[116:117]
	global_store_dwordx4 v[66:67], v[74:77], off
	v_pk_mul_f32 v[230:231], v[62:63], s[98:99]
	v_exp_f32_e32 v230, v230
	v_exp_f32_e32 v231, v231
	v_add_f32_e32 v230, 1.0, v230
	v_add_f32_e32 v231, 1.0, v231
	v_rcp_f32_e32 v230, v230
	v_rcp_f32_e32 v231, v231
	v_mul_f32_e32 v234, v62, v230
	v_mul_f32_e32 v235, v63, v231
	v_pk_mul_f32 v[234:235], v[234:235], v[58:59]
	v_cvt_pk_bf16_f32 v58, v234, v235
	v_pk_mul_f32 v[230:231], v[64:65], s[98:99]
	v_exp_f32_e32 v230, v230
	v_exp_f32_e32 v231, v231
	v_add_f32_e32 v230, 1.0, v230
	v_add_f32_e32 v231, 1.0, v231
	v_rcp_f32_e32 v230, v230
	v_rcp_f32_e32 v231, v231
	v_mul_f32_e32 v236, v64, v230
	v_mul_f32_e32 v237, v65, v231
	v_pk_mul_f32 v[236:237], v[236:237], v[60:61]
	v_cvt_pk_bf16_f32 v59, v236, v237
	v_pk_mul_f32 v[230:231], v[54:55], s[98:99]
	v_exp_f32_e32 v230, v230
	v_exp_f32_e32 v231, v231
	v_add_f32_e32 v230, 1.0, v230
	v_add_f32_e32 v231, 1.0, v231
	v_rcp_f32_e32 v230, v230
	v_rcp_f32_e32 v231, v231
	v_mul_f32_e32 v238, v54, v230
	v_mul_f32_e32 v239, v55, v231
	v_pk_mul_f32 v[238:239], v[238:239], v[50:51]
	v_cvt_pk_bf16_f32 v60, v238, v239
	v_pk_mul_f32 v[230:231], v[56:57], s[98:99]
	v_exp_f32_e32 v230, v230
	v_exp_f32_e32 v231, v231
	v_add_f32_e32 v230, 1.0, v230
	v_add_f32_e32 v231, 1.0, v231
	v_rcp_f32_e32 v230, v230
	v_rcp_f32_e32 v231, v231
	v_mul_f32_e32 v240, v56, v230
	v_mul_f32_e32 v241, v57, v231
	v_pk_mul_f32 v[240:241], v[240:241], v[52:53]
	v_add_u32_e32 v66, 0x80, v148
	v_cvt_pk_bf16_f32 v61, v240, v241
	v_mad_i64_i32 v[50:51], s[42:43], v66, s59, v[114:115]
	v_lshl_add_u64 v[50:51], v[50:51], 0, v[116:117]
	global_store_dwordx4 v[50:51], v[58:61], off
	v_pk_mul_f32 v[230:231], v[46:47], s[98:99]
	v_exp_f32_e32 v230, v230
	v_exp_f32_e32 v231, v231
	v_add_f32_e32 v230, 1.0, v230
	v_add_f32_e32 v231, 1.0, v231
	v_rcp_f32_e32 v230, v230
	v_rcp_f32_e32 v231, v231
	v_mul_f32_e32 v234, v46, v230
	v_mul_f32_e32 v235, v47, v231
	v_pk_mul_f32 v[234:235], v[234:235], v[42:43]
	v_cvt_pk_bf16_f32 v42, v234, v235
	v_pk_mul_f32 v[230:231], v[48:49], s[98:99]
	v_exp_f32_e32 v230, v230
	v_exp_f32_e32 v231, v231
	v_add_f32_e32 v230, 1.0, v230
	v_add_f32_e32 v231, 1.0, v231
	v_rcp_f32_e32 v230, v230
	v_rcp_f32_e32 v231, v231
	v_mul_f32_e32 v236, v48, v230
	v_mul_f32_e32 v237, v49, v231
	v_pk_mul_f32 v[236:237], v[236:237], v[44:45]
	v_cvt_pk_bf16_f32 v43, v236, v237
	v_pk_mul_f32 v[230:231], v[38:39], s[98:99]
	v_exp_f32_e32 v230, v230
	v_exp_f32_e32 v231, v231
	v_add_f32_e32 v230, 1.0, v230
	v_add_f32_e32 v231, 1.0, v231
	v_rcp_f32_e32 v230, v230
	v_rcp_f32_e32 v231, v231
	v_mul_f32_e32 v238, v38, v230
	v_mul_f32_e32 v239, v39, v231
	v_pk_mul_f32 v[238:239], v[238:239], v[34:35]
	v_cvt_pk_bf16_f32 v44, v238, v239
	v_pk_mul_f32 v[230:231], v[40:41], s[98:99]
	v_exp_f32_e32 v230, v230
	v_exp_f32_e32 v231, v231
	v_add_f32_e32 v230, 1.0, v230
	v_add_f32_e32 v231, 1.0, v231
	v_rcp_f32_e32 v230, v230
	v_rcp_f32_e32 v231, v231
	v_mul_f32_e32 v240, v40, v230
	v_mul_f32_e32 v241, v41, v231
	v_pk_mul_f32 v[240:241], v[240:241], v[36:37]
	v_cvt_pk_bf16_f32 v45, v240, v241
	v_add_u32_e32 v34, 0x90, v148
	v_mad_i64_i32 v[34:35], s[42:43], v34, s59, v[114:115]
	v_lshl_add_u64 v[34:35], v[34:35], 0, v[116:117]
	global_store_dwordx4 v[34:35], v[42:45], off
	v_pk_mul_f32 v[230:231], v[30:31], s[98:99]
	v_exp_f32_e32 v230, v230
	v_exp_f32_e32 v231, v231
	v_add_f32_e32 v230, 1.0, v230
	v_add_f32_e32 v231, 1.0, v231
	v_rcp_f32_e32 v230, v230
	v_rcp_f32_e32 v231, v231
	v_mul_f32_e32 v234, v30, v230
	v_mul_f32_e32 v235, v31, v231
	v_pk_mul_f32 v[234:235], v[234:235], v[26:27]
	v_cvt_pk_bf16_f32 v26, v234, v235
	v_pk_mul_f32 v[230:231], v[32:33], s[98:99]
	v_exp_f32_e32 v230, v230
	v_exp_f32_e32 v231, v231
	v_add_f32_e32 v230, 1.0, v230
	v_add_f32_e32 v231, 1.0, v231
	v_rcp_f32_e32 v230, v230
	v_rcp_f32_e32 v231, v231
	v_mul_f32_e32 v236, v32, v230
	v_mul_f32_e32 v237, v33, v231
	v_pk_mul_f32 v[236:237], v[236:237], v[28:29]
	v_cvt_pk_bf16_f32 v27, v236, v237
	v_pk_mul_f32 v[230:231], v[22:23], s[98:99]
	v_exp_f32_e32 v230, v230
	v_exp_f32_e32 v231, v231
	v_add_f32_e32 v230, 1.0, v230
	v_add_f32_e32 v231, 1.0, v231
	v_rcp_f32_e32 v230, v230
	v_rcp_f32_e32 v231, v231
	v_mul_f32_e32 v238, v22, v230
	v_mul_f32_e32 v239, v23, v231
	v_pk_mul_f32 v[238:239], v[238:239], v[18:19]
	v_cvt_pk_bf16_f32 v28, v238, v239
	v_pk_mul_f32 v[230:231], v[24:25], s[98:99]
	v_exp_f32_e32 v230, v230
	v_exp_f32_e32 v231, v231
	v_add_f32_e32 v230, 1.0, v230
	v_add_f32_e32 v231, 1.0, v231
	v_rcp_f32_e32 v230, v230
	v_rcp_f32_e32 v231, v231
	v_mul_f32_e32 v240, v24, v230
	v_mul_f32_e32 v241, v25, v231
	v_pk_mul_f32 v[240:241], v[240:241], v[20:21]
	v_cvt_pk_bf16_f32 v29, v240, v241
	v_add_u32_e32 v18, 0xa0, v148
	v_mad_i64_i32 v[18:19], s[42:43], v18, s59, v[114:115]
	v_lshl_add_u64 v[18:19], v[18:19], 0, v[116:117]
	global_store_dwordx4 v[18:19], v[26:29], off
	v_pk_mul_f32 v[230:231], v[14:15], s[98:99]
	v_exp_f32_e32 v230, v230
	v_exp_f32_e32 v231, v231
	v_add_f32_e32 v230, 1.0, v230
	v_add_f32_e32 v231, 1.0, v231
	v_rcp_f32_e32 v230, v230
	v_rcp_f32_e32 v231, v231
	v_mul_f32_e32 v234, v14, v230
	v_mul_f32_e32 v235, v15, v231
	v_pk_mul_f32 v[234:235], v[234:235], v[10:11]
	v_cvt_pk_bf16_f32 v10, v234, v235
	v_pk_mul_f32 v[230:231], v[16:17], s[98:99]
	v_exp_f32_e32 v230, v230
	v_exp_f32_e32 v231, v231
	v_add_f32_e32 v230, 1.0, v230
	v_add_f32_e32 v231, 1.0, v231
	v_rcp_f32_e32 v230, v230
	v_rcp_f32_e32 v231, v231
	v_mul_f32_e32 v236, v16, v230
	v_mul_f32_e32 v237, v17, v231
	v_pk_mul_f32 v[236:237], v[236:237], v[12:13]
	v_cvt_pk_bf16_f32 v11, v236, v237
	v_pk_mul_f32 v[230:231], v[6:7], s[98:99]
	v_exp_f32_e32 v230, v230
	v_exp_f32_e32 v231, v231
	v_add_f32_e32 v230, 1.0, v230
	v_add_f32_e32 v231, 1.0, v231
	v_rcp_f32_e32 v230, v230
	v_rcp_f32_e32 v231, v231
	v_mul_f32_e32 v238, v6, v230
	v_mul_f32_e32 v239, v7, v231
	v_pk_mul_f32 v[238:239], v[238:239], v[2:3]
	v_cvt_pk_bf16_f32 v12, v238, v239
	v_pk_mul_f32 v[230:231], v[8:9], s[98:99]
	v_exp_f32_e32 v230, v230
	v_exp_f32_e32 v231, v231
	v_add_f32_e32 v230, 1.0, v230
	v_add_f32_e32 v231, 1.0, v231
	v_rcp_f32_e32 v230, v230
	v_rcp_f32_e32 v231, v231
	v_mul_f32_e32 v240, v8, v230
	v_mul_f32_e32 v241, v9, v231
	v_pk_mul_f32 v[240:241], v[240:241], v[4:5]
	v_cvt_pk_bf16_f32 v13, v240, v241
	v_add_u32_e32 v2, 0xb0, v148
	v_mad_i64_i32 v[2:3], s[42:43], v2, s59, v[114:115]
	v_lshl_add_u64 v[2:3], v[2:3], 0, v[116:117]
	s_mov_b64 s[42:43], -1
	s_and_b64 vcc, exec, s[38:39]
	global_store_dwordx4 v[2:3], v[10:13], off
	s_cbranch_vccz .LBB0_5811
	s_andn2_b64 vcc, exec, s[6:7]
	s_cbranch_vccnz .LBB0_5810
	s_barrier
	s_branch .LBB0_5810
